# v042 + LDS-DMA loads use SGPR-base + VGPR-offset addressing where possible (drops 64-bit VALU adds in the load blocks)
# speedup vs baseline: 1.0182x; 1.0113x over previous
.LBB0_134:
	s_add_u32 s28, s66, 0xfffc0080
	s_addc_u32 s29, s67, -1
	s_add_i32 s88, 0, 0x10000
	v_add_u32_e32 v152, s88, v191
	ds_read_b128 v[128:131], v152
	ds_read_b128 v[132:135], v152 offset:1024
	ds_read_b128 v[148:151], v152 offset:2048
	ds_read_b128 v[152:155], v152 offset:3072
	s_cmp_eq_u32 vcc_lo, 12
	s_cselect_b32 s71, s5, s29
	s_cselect_b32 s70, s7, s28
	s_cselect_b32 s69, s17, s91
	s_cselect_b32 s68, s19, s85
	s_add_i32 m0, s73, 0xc000
	ds_read_b128 v[156:159], v192
	ds_read_b128 v[164:167], v192 offset:2048
	ds_read_b128 v[194:197], v192 offset:4096
	ds_read_b128 v[202:205], v192 offset:6144
	ds_read_b128 v[160:163], v192 offset:1024
	ds_read_b128 v[168:171], v192 offset:3072
	ds_read_b128 v[198:201], v192 offset:5120
	ds_read_b128 v[206:209], v192 offset:7168
	global_load_lds_dwordx4 v144, s[66:67]
	v_lshl_add_u64 v[172:173], s[66:67], 0, v[146:147]
	s_add_i32 m0, s73, 0xe000
	s_nop 0
	global_load_lds_dwordx4 v[172:173], off
	s_waitcnt lgkmcnt(8)
	s_barrier
	s_waitcnt lgkmcnt(7)
	v_mfma_f32_16x16x32_bf16 v[124:127], v[128:131], v[156:159], v[124:127]
	v_mfma_f32_16x16x32_bf16 v[120:123], v[148:151], v[156:159], v[120:123]
	s_waitcnt lgkmcnt(6)
	v_mfma_f32_16x16x32_bf16 v[108:111], v[128:131], v[164:167], v[108:111]
	v_mfma_f32_16x16x32_bf16 v[104:107], v[148:151], v[164:167], v[104:107]
	s_waitcnt lgkmcnt(5)
	v_mfma_f32_16x16x32_bf16 v[92:95], v[128:131], v[194:197], v[92:95]
	v_mfma_f32_16x16x32_bf16 v[88:91], v[148:151], v[194:197], v[88:91]
	s_waitcnt lgkmcnt(4)
	v_mfma_f32_16x16x32_bf16 v[76:79], v[128:131], v[202:205], v[76:79]
	v_mfma_f32_16x16x32_bf16 v[72:75], v[148:151], v[202:205], v[72:75]
	s_waitcnt lgkmcnt(3)
	v_mfma_f32_16x16x32_bf16 v[124:127], v[132:135], v[160:163], v[124:127]
	v_mfma_f32_16x16x32_bf16 v[120:123], v[152:155], v[160:163], v[120:123]
	s_waitcnt lgkmcnt(2)
	v_mfma_f32_16x16x32_bf16 v[108:111], v[132:135], v[168:171], v[108:111]
	v_mfma_f32_16x16x32_bf16 v[104:107], v[152:155], v[168:171], v[104:107]
	s_waitcnt lgkmcnt(1)
	v_mfma_f32_16x16x32_bf16 v[92:95], v[132:135], v[198:201], v[92:95]
	v_mfma_f32_16x16x32_bf16 v[88:91], v[152:155], v[198:201], v[88:91]
	s_waitcnt lgkmcnt(0)
	v_mfma_f32_16x16x32_bf16 v[76:79], v[132:135], v[206:209], v[76:79]
	v_mfma_f32_16x16x32_bf16 v[72:75], v[152:155], v[206:209], v[72:75]
	s_barrier
	s_add_i32 s89, 0, 0x14000
	v_add_u32_e32 v172, s89, v191
	s_add_i32 s28, s88, s72
	ds_read_b128 v[210:213], v172
	ds_read_b128 v[214:217], v172 offset:1024
	ds_read_b128 v[232:235], v172 offset:2048
	ds_read_b128 v[236:239], v172 offset:3072
	v_lshl_add_u64 v[172:173], s[68:69], 0, v[138:139]
	s_mov_b32 m0, s28
	v_lshl_add_u64 v[188:189], s[68:69], 0, v[142:143]
	global_load_lds_dwordx4 v[172:173], off
	s_add_i32 m0, s28, 0x2000
	s_nop 0
	global_load_lds_dwordx4 v[188:189], off
	s_barrier
	s_waitcnt lgkmcnt(3)
	v_mfma_f32_16x16x32_bf16 v[116:119], v[210:213], v[156:159], v[116:119]
	s_waitcnt lgkmcnt(1)
	v_mfma_f32_16x16x32_bf16 v[112:115], v[232:235], v[156:159], v[112:115]
	v_mfma_f32_16x16x32_bf16 v[100:103], v[210:213], v[164:167], v[100:103]
	v_mfma_f32_16x16x32_bf16 v[96:99], v[232:235], v[164:167], v[96:99]
	v_mfma_f32_16x16x32_bf16 v[84:87], v[210:213], v[194:197], v[84:87]
	v_mfma_f32_16x16x32_bf16 v[80:83], v[232:235], v[194:197], v[80:83]
	v_mfma_f32_16x16x32_bf16 v[68:71], v[210:213], v[202:205], v[68:71]
	v_mfma_f32_16x16x32_bf16 v[64:67], v[232:235], v[202:205], v[64:67]
	v_mfma_f32_16x16x32_bf16 v[116:119], v[214:217], v[160:163], v[116:119]
	s_waitcnt lgkmcnt(0)
	v_mfma_f32_16x16x32_bf16 v[112:115], v[236:239], v[160:163], v[112:115]
	v_mfma_f32_16x16x32_bf16 v[100:103], v[214:217], v[168:171], v[100:103]
	v_mfma_f32_16x16x32_bf16 v[96:99], v[236:239], v[168:171], v[96:99]
	v_mfma_f32_16x16x32_bf16 v[84:87], v[214:217], v[198:201], v[84:87]
	v_mfma_f32_16x16x32_bf16 v[80:83], v[236:239], v[198:201], v[80:83]
	v_mfma_f32_16x16x32_bf16 v[68:71], v[214:217], v[206:209], v[68:71]
	v_mfma_f32_16x16x32_bf16 v[64:67], v[236:239], v[206:209], v[64:67]
	s_mov_b32 m0, s73
	v_lshl_add_u64 v[240:241], s[70:71], 0, v[136:137]
	s_barrier
	ds_read_b128 v[156:159], v192 offset:16384
	ds_read_b128 v[164:167], v192 offset:18432
	ds_read_b128 v[194:197], v192 offset:20480
	ds_read_b128 v[202:205], v192 offset:22528
	ds_read_b128 v[160:163], v192 offset:17408
	ds_read_b128 v[168:171], v192 offset:19456
	ds_read_b128 v[198:201], v192 offset:21504
	ds_read_b128 v[206:209], v192 offset:23552
	global_load_lds_dwordx4 v[240:241], off
	v_lshl_add_u64 v[242:243], s[70:71], 0, v[140:141]
	s_mov_b32 m0, s74
	s_nop 0
	global_load_lds_dwordx4 v[242:243], off
	s_barrier
	s_waitcnt lgkmcnt(7)
	v_mfma_f32_16x16x32_bf16 v[60:63], v[128:131], v[156:159], v[60:63]
	v_mfma_f32_16x16x32_bf16 v[56:59], v[148:151], v[156:159], v[56:59]
	s_waitcnt lgkmcnt(6)
	v_mfma_f32_16x16x32_bf16 v[44:47], v[128:131], v[164:167], v[44:47]
	v_mfma_f32_16x16x32_bf16 v[40:43], v[148:151], v[164:167], v[40:43]
	s_waitcnt lgkmcnt(5)
	v_mfma_f32_16x16x32_bf16 v[28:31], v[128:131], v[194:197], v[28:31]
	v_mfma_f32_16x16x32_bf16 v[24:27], v[148:151], v[194:197], v[24:27]
	s_waitcnt lgkmcnt(4)
	v_mfma_f32_16x16x32_bf16 v[12:15], v[128:131], v[202:205], v[12:15]
	v_mfma_f32_16x16x32_bf16 v[8:11], v[148:151], v[202:205], v[8:11]
	s_waitcnt lgkmcnt(3)
	v_mfma_f32_16x16x32_bf16 v[60:63], v[132:135], v[160:163], v[60:63]
	v_mfma_f32_16x16x32_bf16 v[56:59], v[152:155], v[160:163], v[56:59]
	s_waitcnt lgkmcnt(2)
	v_mfma_f32_16x16x32_bf16 v[44:47], v[132:135], v[168:171], v[44:47]
	v_mfma_f32_16x16x32_bf16 v[40:43], v[152:155], v[168:171], v[40:43]
	s_waitcnt lgkmcnt(1)
	v_mfma_f32_16x16x32_bf16 v[28:31], v[132:135], v[198:201], v[28:31]
	v_mfma_f32_16x16x32_bf16 v[24:27], v[152:155], v[198:201], v[24:27]
	s_waitcnt lgkmcnt(0)
	v_mfma_f32_16x16x32_bf16 v[12:15], v[132:135], v[206:209], v[12:15]
	v_mfma_f32_16x16x32_bf16 v[8:11], v[152:155], v[206:209], v[8:11]
	s_barrier
	s_add_u32 s28, s68, 0x40000
	s_addc_u32 s29, s69, 0
	s_add_i32 s88, s89, s72
	s_mov_b32 m0, s88
	s_nop 0
	global_load_lds_dwordx4 v138, s[28:29]
	s_add_i32 m0, s88, 0x2000
	s_nop 0
	global_load_lds_dwordx4 v142, s[28:29]
	s_waitcnt vmcnt(6)
	s_barrier
	v_mfma_f32_16x16x32_bf16 v[52:55], v[210:213], v[156:159], v[52:55]
	v_mfma_f32_16x16x32_bf16 v[48:51], v[232:235], v[156:159], v[48:51]
	v_mfma_f32_16x16x32_bf16 v[36:39], v[210:213], v[164:167], v[36:39]
	v_mfma_f32_16x16x32_bf16 v[32:35], v[232:235], v[164:167], v[32:35]
	v_mfma_f32_16x16x32_bf16 v[20:23], v[210:213], v[194:197], v[20:23]
	v_mfma_f32_16x16x32_bf16 v[16:19], v[232:235], v[194:197], v[16:19]
	v_mfma_f32_16x16x32_bf16 v[4:7], v[210:213], v[202:205], v[4:7]
	v_mfma_f32_16x16x32_bf16 v[0:3], v[232:235], v[202:205], v[0:3]
	v_mfma_f32_16x16x32_bf16 v[52:55], v[214:217], v[160:163], v[52:55]
	v_mfma_f32_16x16x32_bf16 v[48:51], v[236:239], v[160:163], v[48:51]
	v_mfma_f32_16x16x32_bf16 v[36:39], v[214:217], v[168:171], v[36:39]
	v_mfma_f32_16x16x32_bf16 v[32:35], v[236:239], v[168:171], v[32:35]
	v_mfma_f32_16x16x32_bf16 v[20:23], v[214:217], v[198:201], v[20:23]
	v_mfma_f32_16x16x32_bf16 v[16:19], v[236:239], v[198:201], v[16:19]
	v_mfma_f32_16x16x32_bf16 v[4:7], v[214:217], v[206:209], v[4:7]
	v_mfma_f32_16x16x32_bf16 v[0:3], v[236:239], v[206:209], v[0:3]
	s_add_i32 s88, 0, 0x18000
	v_add_u32_e32 v152, s88, v191
	s_barrier
	ds_read_b128 v[128:131], v152
	ds_read_b128 v[132:135], v152 offset:1024
	ds_read_b128 v[148:151], v152 offset:2048
	ds_read_b128 v[152:155], v152 offset:3072
	s_add_u32 s28, s70, 0x40000
	s_addc_u32 s29, s71, 0
	s_mov_b32 m0, s75
	ds_read_b128 v[156:159], v192 offset:32768
	ds_read_b128 v[164:167], v192 offset:34816
	ds_read_b128 v[194:197], v192 offset:36864
	ds_read_b128 v[202:205], v192 offset:38912
	ds_read_b128 v[160:163], v192 offset:33792
	ds_read_b128 v[168:171], v192 offset:35840
	ds_read_b128 v[198:201], v192 offset:37888
	ds_read_b128 v[206:209], v192 offset:39936
	global_load_lds_dwordx4 v136, s[28:29]
	s_mov_b32 m0, s76
	s_nop 0
	global_load_lds_dwordx4 v140, s[28:29]
	s_waitcnt lgkmcnt(8)
	s_barrier
	s_waitcnt lgkmcnt(7)
	v_mfma_f32_16x16x32_bf16 v[124:127], v[128:131], v[156:159], v[124:127]
	v_mfma_f32_16x16x32_bf16 v[120:123], v[148:151], v[156:159], v[120:123]
	s_waitcnt lgkmcnt(6)
	v_mfma_f32_16x16x32_bf16 v[108:111], v[128:131], v[164:167], v[108:111]
	v_mfma_f32_16x16x32_bf16 v[104:107], v[148:151], v[164:167], v[104:107]
	s_waitcnt lgkmcnt(5)
	v_mfma_f32_16x16x32_bf16 v[92:95], v[128:131], v[194:197], v[92:95]
	v_mfma_f32_16x16x32_bf16 v[88:91], v[148:151], v[194:197], v[88:91]
	s_waitcnt lgkmcnt(4)
	v_mfma_f32_16x16x32_bf16 v[76:79], v[128:131], v[202:205], v[76:79]
	v_mfma_f32_16x16x32_bf16 v[72:75], v[148:151], v[202:205], v[72:75]
	s_waitcnt lgkmcnt(3)
	v_mfma_f32_16x16x32_bf16 v[124:127], v[132:135], v[160:163], v[124:127]
	v_mfma_f32_16x16x32_bf16 v[120:123], v[152:155], v[160:163], v[120:123]
	s_waitcnt lgkmcnt(2)
	v_mfma_f32_16x16x32_bf16 v[108:111], v[132:135], v[168:171], v[108:111]
	v_mfma_f32_16x16x32_bf16 v[104:107], v[152:155], v[168:171], v[104:107]
	s_waitcnt lgkmcnt(1)
	v_mfma_f32_16x16x32_bf16 v[92:95], v[132:135], v[198:201], v[92:95]
	v_mfma_f32_16x16x32_bf16 v[88:91], v[152:155], v[198:201], v[88:91]
	s_waitcnt lgkmcnt(0)
	v_mfma_f32_16x16x32_bf16 v[76:79], v[132:135], v[206:209], v[76:79]
	v_mfma_f32_16x16x32_bf16 v[72:75], v[152:155], v[206:209], v[72:75]
	s_barrier
	s_add_i32 s70, 0, 0x1c000
	s_add_i32 s28, s88, s72
	v_add_u32_e32 v174, s70, v191
	v_lshl_add_u64 v[172:173], v[172:173], 0, s[40:41]
	s_mov_b32 m0, s28
	ds_read_b128 v[210:213], v174
	ds_read_b128 v[214:217], v174 offset:1024
	ds_read_b128 v[232:235], v174 offset:2048
	ds_read_b128 v[236:239], v174 offset:3072
	global_load_lds_dwordx4 v[172:173], off
	v_lshl_add_u64 v[172:173], v[188:189], 0, s[40:41]
	s_add_i32 m0, s28, 0x2000
	s_nop 0
	global_load_lds_dwordx4 v[172:173], off
	s_barrier
	s_waitcnt lgkmcnt(3)
	v_mfma_f32_16x16x32_bf16 v[116:119], v[210:213], v[156:159], v[116:119]
	s_waitcnt lgkmcnt(1)
	v_mfma_f32_16x16x32_bf16 v[112:115], v[232:235], v[156:159], v[112:115]
	v_mfma_f32_16x16x32_bf16 v[100:103], v[210:213], v[164:167], v[100:103]
	v_mfma_f32_16x16x32_bf16 v[96:99], v[232:235], v[164:167], v[96:99]
	v_mfma_f32_16x16x32_bf16 v[84:87], v[210:213], v[194:197], v[84:87]
	v_mfma_f32_16x16x32_bf16 v[80:83], v[232:235], v[194:197], v[80:83]
	v_mfma_f32_16x16x32_bf16 v[68:71], v[210:213], v[202:205], v[68:71]
	v_mfma_f32_16x16x32_bf16 v[64:67], v[232:235], v[202:205], v[64:67]
	v_mfma_f32_16x16x32_bf16 v[116:119], v[214:217], v[160:163], v[116:119]
	s_waitcnt lgkmcnt(0)
	v_mfma_f32_16x16x32_bf16 v[112:115], v[236:239], v[160:163], v[112:115]
	v_mfma_f32_16x16x32_bf16 v[100:103], v[214:217], v[168:171], v[100:103]
	v_mfma_f32_16x16x32_bf16 v[96:99], v[236:239], v[168:171], v[96:99]
	v_mfma_f32_16x16x32_bf16 v[84:87], v[214:217], v[198:201], v[84:87]
	v_mfma_f32_16x16x32_bf16 v[80:83], v[236:239], v[198:201], v[80:83]
	v_mfma_f32_16x16x32_bf16 v[68:71], v[214:217], v[206:209], v[68:71]
	v_mfma_f32_16x16x32_bf16 v[64:67], v[236:239], v[206:209], v[64:67]
	s_mov_b32 m0, s79
	v_lshl_add_u64 v[172:173], v[240:241], 0, s[40:41]
	s_barrier
	ds_read_b128 v[156:159], v192 offset:49152
	ds_read_b128 v[164:167], v192 offset:51200
	ds_read_b128 v[194:197], v192 offset:53248
	ds_read_b128 v[202:205], v192 offset:55296
	ds_read_b128 v[160:163], v192 offset:50176
	ds_read_b128 v[168:171], v192 offset:52224
	ds_read_b128 v[198:201], v192 offset:54272
	ds_read_b128 v[206:209], v192 offset:56320
	global_load_lds_dwordx4 v[172:173], off
	v_lshl_add_u64 v[172:173], v[242:243], 0, s[40:41]
	s_mov_b32 m0, s80
	s_nop 0
	global_load_lds_dwordx4 v[172:173], off
	s_barrier
	s_waitcnt lgkmcnt(7)
	v_mfma_f32_16x16x32_bf16 v[60:63], v[128:131], v[156:159], v[60:63]
	v_mfma_f32_16x16x32_bf16 v[56:59], v[148:151], v[156:159], v[56:59]
	s_waitcnt lgkmcnt(6)
	v_mfma_f32_16x16x32_bf16 v[44:47], v[128:131], v[164:167], v[44:47]
	v_mfma_f32_16x16x32_bf16 v[40:43], v[148:151], v[164:167], v[40:43]
	s_waitcnt lgkmcnt(5)
	v_mfma_f32_16x16x32_bf16 v[28:31], v[128:131], v[194:197], v[28:31]
	v_mfma_f32_16x16x32_bf16 v[24:27], v[148:151], v[194:197], v[24:27]
	s_waitcnt lgkmcnt(4)
	v_mfma_f32_16x16x32_bf16 v[12:15], v[128:131], v[202:205], v[12:15]
	v_mfma_f32_16x16x32_bf16 v[8:11], v[148:151], v[202:205], v[8:11]
	s_waitcnt lgkmcnt(3)
	v_mfma_f32_16x16x32_bf16 v[60:63], v[132:135], v[160:163], v[60:63]
	v_mfma_f32_16x16x32_bf16 v[56:59], v[152:155], v[160:163], v[56:59]
	s_waitcnt lgkmcnt(2)
	v_mfma_f32_16x16x32_bf16 v[44:47], v[132:135], v[168:171], v[44:47]
	v_mfma_f32_16x16x32_bf16 v[40:43], v[152:155], v[168:171], v[40:43]
	s_waitcnt lgkmcnt(1)
	v_mfma_f32_16x16x32_bf16 v[28:31], v[132:135], v[198:201], v[28:31]
	v_mfma_f32_16x16x32_bf16 v[24:27], v[152:155], v[198:201], v[24:27]
	s_waitcnt lgkmcnt(0)
	v_mfma_f32_16x16x32_bf16 v[12:15], v[132:135], v[206:209], v[12:15]
	v_mfma_f32_16x16x32_bf16 v[8:11], v[152:155], v[206:209], v[8:11]
	s_barrier
	s_add_u32 s28, s68, 0x40080
	s_addc_u32 s29, s69, 0
	s_add_i32 s68, s70, s72
	s_mov_b32 m0, s68
	s_nop 0
	global_load_lds_dwordx4 v138, s[28:29]
	s_add_i32 m0, s68, 0x2000
	s_nop 0
	global_load_lds_dwordx4 v142, s[28:29]
	s_waitcnt vmcnt(6)
	s_barrier
	v_mfma_f32_16x16x32_bf16 v[52:55], v[210:213], v[156:159], v[52:55]
	v_mfma_f32_16x16x32_bf16 v[48:51], v[232:235], v[156:159], v[48:51]
	v_mfma_f32_16x16x32_bf16 v[36:39], v[210:213], v[164:167], v[36:39]
	v_mfma_f32_16x16x32_bf16 v[32:35], v[232:235], v[164:167], v[32:35]
	v_mfma_f32_16x16x32_bf16 v[20:23], v[210:213], v[194:197], v[20:23]
	v_mfma_f32_16x16x32_bf16 v[16:19], v[232:235], v[194:197], v[16:19]
	v_mfma_f32_16x16x32_bf16 v[4:7], v[210:213], v[202:205], v[4:7]
	v_mfma_f32_16x16x32_bf16 v[0:3], v[232:235], v[202:205], v[0:3]
	v_mfma_f32_16x16x32_bf16 v[52:55], v[214:217], v[160:163], v[52:55]
	v_mfma_f32_16x16x32_bf16 v[48:51], v[236:239], v[160:163], v[48:51]
	v_mfma_f32_16x16x32_bf16 v[36:39], v[214:217], v[168:171], v[36:39]
	v_mfma_f32_16x16x32_bf16 v[32:35], v[236:239], v[168:171], v[32:35]
	v_mfma_f32_16x16x32_bf16 v[20:23], v[214:217], v[198:201], v[20:23]
	v_mfma_f32_16x16x32_bf16 v[16:19], v[236:239], v[198:201], v[16:19]
	v_mfma_f32_16x16x32_bf16 v[4:7], v[214:217], v[206:209], v[4:7]
	v_mfma_f32_16x16x32_bf16 v[0:3], v[236:239], v[206:209], v[0:3]
	s_add_i32 vcc_lo, vcc_lo, 2
	s_add_u32 s66, s66, 0x100
	s_addc_u32 s67, s67, 0
	s_add_u32 s85, s85, 0x100
	s_addc_u32 s91, s91, 0
	s_cmp_lt_u32 vcc_lo, 14
	s_barrier
	s_cbranch_scc1 .LBB0_134
	s_lshl_b32 s4, s4, 8
	v_mov_b32_e32 v176, v175
	v_mov_b32_e32 v188, v190
	s_add_i32 s4, s4, s77
	s_cmp_gt_i32 s6, 7
	v_add_u32_e32 v148, s4, v176
	v_lshlrev_b32_e32 v128, 2, v188
	v_ashrrev_i32_e32 v129, 31, v128
	v_ashrrev_i32_e32 v149, 31, v148
	v_lshl_add_u64 v[128:129], v[128:129], 2, s[8:9]
	v_lshlrev_b64 v[130:131], 6, v[148:149]
	v_add_u32_e32 v166, 16, v148
	v_lshl_add_u64 v[130:131], v[128:129], 0, v[130:131]
	v_ashrrev_i32_e32 v167, 31, v166
	global_load_dwordx4 v[160:163], v[130:131], off
	v_lshlrev_b64 v[130:131], 6, v[166:167]
	v_lshl_add_u64 v[130:131], v[128:129], 0, v[130:131]
	global_load_dwordx4 v[168:171], v[130:131], off
	v_add_u32_e32 v164, 32, v148
	v_ashrrev_i32_e32 v165, 31, v164
	v_lshlrev_b64 v[130:131], 6, v[164:165]
	v_add_u32_e32 v158, 48, v148
	v_lshl_add_u64 v[130:131], v[128:129], 0, v[130:131]
	v_ashrrev_i32_e32 v159, 31, v158
	global_load_dwordx4 v[194:197], v[130:131], off
	v_lshlrev_b64 v[130:131], 6, v[158:159]
	v_lshl_add_u64 v[130:131], v[128:129], 0, v[130:131]
	global_load_dwordx4 v[198:201], v[130:131], off
	v_add_u32_e32 v156, 0x80, v148
	v_ashrrev_i32_e32 v157, 31, v156
	v_lshlrev_b64 v[130:131], 6, v[156:157]
	v_add_u32_e32 v154, 0x90, v148
	v_lshl_add_u64 v[130:131], v[128:129], 0, v[130:131]
	v_ashrrev_i32_e32 v155, 31, v154
	global_load_dwordx4 v[202:205], v[130:131], off
	v_lshlrev_b64 v[130:131], 6, v[154:155]
	v_add_u32_e32 v152, 0xa0, v148
	v_lshl_add_u64 v[130:131], v[128:129], 0, v[130:131]
	v_ashrrev_i32_e32 v153, 31, v152
	global_load_dwordx4 v[206:209], v[130:131], off
	v_lshlrev_b64 v[130:131], 6, v[152:153]
	v_add_u32_e32 v150, 0xb0, v148
	v_lshl_add_u64 v[130:131], v[128:129], 0, v[130:131]
	v_ashrrev_i32_e32 v151, 31, v150
	global_load_dwordx4 v[132:135], v[130:131], off
	v_lshlrev_b64 v[130:131], 6, v[150:151]
	v_lshl_add_u64 v[128:129], v[128:129], 0, v[130:131]
	global_load_dwordx4 v[128:131], v[128:129], off
	s_cselect_b64 s[66:67], -1, 0
	s_lshl_b32 s7, s6, 8
	s_add_i32 s7, s81, s7
	s_cmp_lt_i32 s6, 8
	s_mov_b64 s[68:69], -1
	s_waitcnt vmcnt(0)
	v_mov_b32_e32 v172, v161
	v_mov_b32_e32 v173, v162
	v_mov_b32_e32 v161, v163
	v_mov_b32_e32 v162, v169
	v_mov_b32_e32 v163, v170
	v_mov_b32_e32 v169, v171
	v_pk_add_f32 v[160:161], v[172:173], v[160:161]
	v_pk_add_f32 v[162:163], v[162:163], v[168:169]
	v_mov_b32_e32 v169, v160
	v_mov_b32_e32 v168, v162
	v_mov_b32_e32 v160, v163
	v_pk_add_f32 v[160:161], v[168:169], v[160:161]
	ds_bpermute_b32 v163, v219, v161
	ds_bpermute_b32 v162, v219, v160
	s_waitcnt lgkmcnt(0)
	v_pk_add_f32 v[160:161], v[160:161], v[162:163]
	ds_bpermute_b32 v163, v218, v161
	ds_bpermute_b32 v162, v218, v160
	s_waitcnt lgkmcnt(0)
	v_pk_add_f32 v[160:161], v[160:161], v[162:163]
	s_nop 0
	v_pk_fma_f32 v[172:173], v[160:161], s[30:31], v[178:179] op_sel_hi:[1,0,0]
	v_mov_b32_e32 v162, v199
	v_mul_f32_e32 v160, 0x4b800000, v173
	v_cmp_gt_f32_e32 vcc, s86, v173
	v_mov_b32_e32 v163, v200
	v_mov_b32_e32 v199, v201
	v_cndmask_b32_e32 v160, v173, v160, vcc
	v_rsq_f32_e32 v160, v160
	v_pk_add_f32 v[162:163], v[162:163], v[198:199]
	v_cmp_gt_f32_e64 s[4:5], s86, v172
	v_mov_b32_e32 v168, v162
	v_mul_f32_e32 v161, 0x45800000, v160
	v_cndmask_b32_e32 v174, v160, v161, vcc
	v_mov_b32_e32 v160, v195
	v_mov_b32_e32 v161, v196
	v_mov_b32_e32 v195, v197
	v_pk_add_f32 v[160:161], v[160:161], v[194:195]
	s_nop 0
	v_mov_b32_e32 v169, v160
	v_mov_b32_e32 v160, v163
	v_pk_add_f32 v[160:161], v[168:169], v[160:161]
	ds_bpermute_b32 v163, v219, v161
	ds_bpermute_b32 v162, v219, v160
	s_waitcnt lgkmcnt(0)
	v_pk_add_f32 v[168:169], v[160:161], v[162:163]
	v_mov_b32_e32 v160, v203
	v_mov_b32_e32 v161, v204
	v_mov_b32_e32 v203, v205
	v_mov_b32_e32 v162, v207
	v_mov_b32_e32 v163, v208
	v_mov_b32_e32 v207, v209
	v_pk_add_f32 v[160:161], v[160:161], v[202:203]
	v_pk_add_f32 v[162:163], v[162:163], v[206:207]
	v_mov_b32_e32 v195, v160
	v_mov_b32_e32 v194, v162
	v_mov_b32_e32 v160, v163
	v_pk_add_f32 v[160:161], v[194:195], v[160:161]
	v_mov_b32_e32 v194, v133
	v_mov_b32_e32 v195, v134
	v_mov_b32_e32 v133, v135
	v_mov_b32_e32 v134, v129
	v_mov_b32_e32 v135, v130
	v_mov_b32_e32 v129, v131
	v_pk_add_f32 v[132:133], v[194:195], v[132:133]
	v_pk_add_f32 v[128:129], v[134:135], v[128:129]
	v_mov_b32_e32 v131, v132
	v_mov_b32_e32 v130, v128
	v_mov_b32_e32 v132, v129
	v_pk_add_f32 v[128:129], v[130:131], v[132:133]
	ds_bpermute_b32 v163, v219, v161
	ds_bpermute_b32 v162, v219, v160
	ds_bpermute_b32 v131, v219, v129
	ds_bpermute_b32 v130, v219, v128
	ds_bpermute_b32 v171, v218, v169
	ds_bpermute_b32 v170, v218, v168
	s_waitcnt lgkmcnt(4)
	v_pk_add_f32 v[160:161], v[160:161], v[162:163]
	ds_bpermute_b32 v163, v218, v161
	s_waitcnt lgkmcnt(3)
	v_pk_add_f32 v[132:133], v[128:129], v[130:131]
	ds_bpermute_b32 v162, v218, v160
	ds_bpermute_b32 v135, v218, v133
	ds_bpermute_b32 v134, v218, v132
	v_lshlrev_b32_e32 v128, 3, v188
	v_add_u32_e32 v130, s7, v128
	v_lshlrev_b64 v[188:189], 11, v[148:149]
	v_ashrrev_i32_e32 v131, 31, v130
	s_cbranch_scc1 .LBB0_137
	v_mul_f32_e32 v196, v120, v174
	v_mul_f32_e32 v197, v121, v174
	v_mul_f32_e32 v198, v122, v174
	v_mul_f32_e32 v199, v123, v174
	v_mul_f32_e32 v129, v124, v174
	v_mul_f32_e32 v149, v125, v174
	v_mul_f32_e32 v173, v126, v174
	v_mul_f32_e32 v193, v127, v174
	v_cvt_pk_bf16_f32 v194, v129, v149
	v_cvt_pk_bf16_f32 v195, v173, v193
	v_cvt_pk_bf16_f32 v196, v196, v197
	v_cvt_pk_bf16_f32 v197, v198, v199
	v_lshl_add_u64 v[198:199], s[12:13], 0, v[188:189]
	v_lshl_add_u64 v[198:199], v[130:131], 1, v[198:199]
	global_store_dwordx4 v[198:199], v[194:197], off
	s_mov_b64 s[68:69], 0
	v_mul_f32_e32 v129, v116, v174
	v_mul_f32_e32 v196, v112, v174
	v_mul_f32_e32 v197, v113, v174
	v_mul_f32_e32 v149, v117, v174
	v_mul_f32_e32 v173, v118, v174
	v_mul_f32_e32 v193, v119, v174
	v_mul_f32_e32 v200, v114, v174
	v_mul_f32_e32 v201, v115, v174
	v_cvt_pk_bf16_f32 v194, v129, v149
	v_cvt_pk_bf16_f32 v195, v173, v193
	v_cvt_pk_bf16_f32 v196, v196, v197
	v_cvt_pk_bf16_f32 v197, v200, v201
	global_store_dwordx4 v[198:199], v[194:197], off offset:256

.LBB0_413:
	s_add_i32 vcc_lo, s62, 2
	s_add_u32 s4, s18, 0x100
	s_addc_u32 s5, s19, 0
	s_add_i32 s28, 0, 0x10000
	v_add_u32_e32 v140, s28, v164
	ds_read_b128 v[128:131], v140
	ds_read_b128 v[132:135], v140 offset:1024
	ds_read_b128 v[136:139], v140 offset:2048
	ds_read_b128 v[140:143], v140 offset:3072
	s_cmp_eq_u32 s13, s62
	s_cselect_b32 s62, s6, s85
	s_cselect_b32 s65, s17, s5
	s_cselect_b32 s64, s16, s4
	s_cselect_b32 s63, s7, s91
	s_add_i32 m0, s69, 0xc000
	ds_read_b128 v[154:157], v165
	ds_read_b128 v[166:169], v165 offset:2048
	ds_read_b128 v[188:191], v165 offset:4096
	ds_read_b128 v[196:199], v165 offset:6144
	ds_read_b128 v[158:161], v165 offset:1024
	ds_read_b128 v[170:173], v165 offset:3072
	ds_read_b128 v[192:195], v165 offset:5120
	ds_read_b128 v[200:203], v165 offset:7168
	global_load_lds_dwordx4 v150, s[18:19]
	v_lshl_add_u64 v[174:175], s[18:19], 0, v[152:153]
	s_add_i32 m0, s69, 0xe000
	s_nop 0
	global_load_lds_dwordx4 v[174:175], off
	s_waitcnt lgkmcnt(8)
	s_barrier
	s_waitcnt lgkmcnt(7)
	v_mfma_f32_16x16x32_bf16 v[124:127], v[128:131], v[154:157], v[124:127]
	v_mfma_f32_16x16x32_bf16 v[120:123], v[136:139], v[154:157], v[120:123]
	s_waitcnt lgkmcnt(6)
	v_mfma_f32_16x16x32_bf16 v[108:111], v[128:131], v[166:169], v[108:111]
	v_mfma_f32_16x16x32_bf16 v[104:107], v[136:139], v[166:169], v[104:107]
	s_waitcnt lgkmcnt(5)
	v_mfma_f32_16x16x32_bf16 v[92:95], v[128:131], v[188:191], v[92:95]
	v_mfma_f32_16x16x32_bf16 v[88:91], v[136:139], v[188:191], v[88:91]
	s_waitcnt lgkmcnt(4)
	v_mfma_f32_16x16x32_bf16 v[76:79], v[128:131], v[196:199], v[76:79]
	v_mfma_f32_16x16x32_bf16 v[72:75], v[136:139], v[196:199], v[72:75]
	s_waitcnt lgkmcnt(3)
	v_mfma_f32_16x16x32_bf16 v[124:127], v[132:135], v[158:161], v[124:127]
	v_mfma_f32_16x16x32_bf16 v[120:123], v[140:143], v[158:161], v[120:123]
	s_waitcnt lgkmcnt(2)
	v_mfma_f32_16x16x32_bf16 v[108:111], v[132:135], v[170:173], v[108:111]
	v_mfma_f32_16x16x32_bf16 v[104:107], v[140:143], v[170:173], v[104:107]
	s_waitcnt lgkmcnt(1)
	v_mfma_f32_16x16x32_bf16 v[92:95], v[132:135], v[192:195], v[92:95]
	v_mfma_f32_16x16x32_bf16 v[88:91], v[140:143], v[192:195], v[88:91]
	s_waitcnt lgkmcnt(0)
	v_mfma_f32_16x16x32_bf16 v[76:79], v[132:135], v[200:203], v[76:79]
	v_mfma_f32_16x16x32_bf16 v[72:75], v[140:143], v[200:203], v[72:75]
	s_barrier
	s_add_i32 s29, 0, 0x14000
	v_add_u32_e32 v174, s29, v164
	s_add_i32 s18, s28, s68
	ds_read_b128 v[204:207], v174
	ds_read_b128 v[208:211], v174 offset:1024
	ds_read_b128 v[212:215], v174 offset:2048
	ds_read_b128 v[232:235], v174 offset:3072
	v_lshl_add_u64 v[174:175], s[62:63], 0, v[176:177]
	s_mov_b32 m0, s18
	v_lshl_add_u64 v[216:217], s[62:63], 0, v[148:149]
	global_load_lds_dwordx4 v[174:175], off
	s_add_i32 m0, s18, 0x2000
	s_nop 0
	global_load_lds_dwordx4 v[216:217], off
	s_barrier
	s_waitcnt lgkmcnt(3)
	v_mfma_f32_16x16x32_bf16 v[116:119], v[204:207], v[154:157], v[116:119]
	s_waitcnt lgkmcnt(1)
	v_mfma_f32_16x16x32_bf16 v[112:115], v[212:215], v[154:157], v[112:115]
	v_mfma_f32_16x16x32_bf16 v[100:103], v[204:207], v[166:169], v[100:103]
	v_mfma_f32_16x16x32_bf16 v[96:99], v[212:215], v[166:169], v[96:99]
	v_mfma_f32_16x16x32_bf16 v[84:87], v[204:207], v[188:191], v[84:87]
	v_mfma_f32_16x16x32_bf16 v[80:83], v[212:215], v[188:191], v[80:83]
	v_mfma_f32_16x16x32_bf16 v[68:71], v[204:207], v[196:199], v[68:71]
	v_mfma_f32_16x16x32_bf16 v[64:67], v[212:215], v[196:199], v[64:67]
	v_mfma_f32_16x16x32_bf16 v[116:119], v[208:211], v[158:161], v[116:119]
	s_waitcnt lgkmcnt(0)
	v_mfma_f32_16x16x32_bf16 v[112:115], v[232:235], v[158:161], v[112:115]
	v_mfma_f32_16x16x32_bf16 v[100:103], v[208:211], v[170:173], v[100:103]
	v_mfma_f32_16x16x32_bf16 v[96:99], v[232:235], v[170:173], v[96:99]
	v_mfma_f32_16x16x32_bf16 v[84:87], v[208:211], v[192:195], v[84:87]
	v_mfma_f32_16x16x32_bf16 v[80:83], v[232:235], v[192:195], v[80:83]
	v_mfma_f32_16x16x32_bf16 v[68:71], v[208:211], v[200:203], v[68:71]
	v_mfma_f32_16x16x32_bf16 v[64:67], v[232:235], v[200:203], v[64:67]
	s_mov_b32 m0, s69
	v_lshl_add_u64 v[236:237], s[64:65], 0, v[144:145]
	s_barrier
	ds_read_b128 v[154:157], v165 offset:16384
	ds_read_b128 v[166:169], v165 offset:18432
	ds_read_b128 v[188:191], v165 offset:20480
	ds_read_b128 v[196:199], v165 offset:22528
	ds_read_b128 v[158:161], v165 offset:17408
	ds_read_b128 v[170:173], v165 offset:19456
	ds_read_b128 v[192:195], v165 offset:21504
	ds_read_b128 v[200:203], v165 offset:23552
	global_load_lds_dwordx4 v[236:237], off
	v_lshl_add_u64 v[238:239], s[64:65], 0, v[146:147]
	s_mov_b32 m0, s70
	s_nop 0
	global_load_lds_dwordx4 v[238:239], off
	s_barrier
	s_waitcnt lgkmcnt(7)
	v_mfma_f32_16x16x32_bf16 v[60:63], v[128:131], v[154:157], v[60:63]
	v_mfma_f32_16x16x32_bf16 v[56:59], v[136:139], v[154:157], v[56:59]
	s_waitcnt lgkmcnt(6)
	v_mfma_f32_16x16x32_bf16 v[44:47], v[128:131], v[166:169], v[44:47]
	v_mfma_f32_16x16x32_bf16 v[40:43], v[136:139], v[166:169], v[40:43]
	s_waitcnt lgkmcnt(5)
	v_mfma_f32_16x16x32_bf16 v[28:31], v[128:131], v[188:191], v[28:31]
	v_mfma_f32_16x16x32_bf16 v[24:27], v[136:139], v[188:191], v[24:27]
	s_waitcnt lgkmcnt(4)
	v_mfma_f32_16x16x32_bf16 v[12:15], v[128:131], v[196:199], v[12:15]
	v_mfma_f32_16x16x32_bf16 v[8:11], v[136:139], v[196:199], v[8:11]
	s_waitcnt lgkmcnt(3)
	v_mfma_f32_16x16x32_bf16 v[60:63], v[132:135], v[158:161], v[60:63]
	v_mfma_f32_16x16x32_bf16 v[56:59], v[140:143], v[158:161], v[56:59]
	s_waitcnt lgkmcnt(2)
	v_mfma_f32_16x16x32_bf16 v[44:47], v[132:135], v[170:173], v[44:47]
	v_mfma_f32_16x16x32_bf16 v[40:43], v[140:143], v[170:173], v[40:43]
	s_waitcnt lgkmcnt(1)
	v_mfma_f32_16x16x32_bf16 v[28:31], v[132:135], v[192:195], v[28:31]
	v_mfma_f32_16x16x32_bf16 v[24:27], v[140:143], v[192:195], v[24:27]
	s_waitcnt lgkmcnt(0)
	v_mfma_f32_16x16x32_bf16 v[12:15], v[132:135], v[200:203], v[12:15]
	v_mfma_f32_16x16x32_bf16 v[8:11], v[140:143], v[200:203], v[8:11]
	s_barrier
	s_add_u32 s18, s62, 0x18000
	s_addc_u32 s19, s63, 0
	s_add_i32 s28, s29, s68
	s_mov_b32 m0, s28
	s_nop 0
	global_load_lds_dwordx4 v176, s[18:19]
	s_add_i32 m0, s28, 0x2000
	s_nop 0
	global_load_lds_dwordx4 v148, s[18:19]
	s_waitcnt vmcnt(6)
	s_barrier
	v_mfma_f32_16x16x32_bf16 v[52:55], v[204:207], v[154:157], v[52:55]
	v_mfma_f32_16x16x32_bf16 v[48:51], v[212:215], v[154:157], v[48:51]
	v_mfma_f32_16x16x32_bf16 v[36:39], v[204:207], v[166:169], v[36:39]
	v_mfma_f32_16x16x32_bf16 v[32:35], v[212:215], v[166:169], v[32:35]
	v_mfma_f32_16x16x32_bf16 v[20:23], v[204:207], v[188:191], v[20:23]
	v_mfma_f32_16x16x32_bf16 v[16:19], v[212:215], v[188:191], v[16:19]
	v_mfma_f32_16x16x32_bf16 v[4:7], v[204:207], v[196:199], v[4:7]
	v_mfma_f32_16x16x32_bf16 v[0:3], v[212:215], v[196:199], v[0:3]
	v_mfma_f32_16x16x32_bf16 v[52:55], v[208:211], v[158:161], v[52:55]
	v_mfma_f32_16x16x32_bf16 v[48:51], v[232:235], v[158:161], v[48:51]
	v_mfma_f32_16x16x32_bf16 v[36:39], v[208:211], v[170:173], v[36:39]
	v_mfma_f32_16x16x32_bf16 v[32:35], v[232:235], v[170:173], v[32:35]
	v_mfma_f32_16x16x32_bf16 v[20:23], v[208:211], v[192:195], v[20:23]
	v_mfma_f32_16x16x32_bf16 v[16:19], v[232:235], v[192:195], v[16:19]
	v_mfma_f32_16x16x32_bf16 v[4:7], v[208:211], v[200:203], v[4:7]
	v_mfma_f32_16x16x32_bf16 v[0:3], v[232:235], v[200:203], v[0:3]
	s_add_i32 s28, 0, 0x18000
	v_add_u32_e32 v140, s28, v164
	s_barrier
	ds_read_b128 v[128:131], v140
	ds_read_b128 v[132:135], v140 offset:1024
	ds_read_b128 v[136:139], v140 offset:2048
	ds_read_b128 v[140:143], v140 offset:3072
	s_add_u32 s18, s64, 0x18000
	s_addc_u32 s19, s65, 0
	s_mov_b32 m0, s71
	ds_read_b128 v[154:157], v165 offset:32768
	ds_read_b128 v[166:169], v165 offset:34816
	ds_read_b128 v[188:191], v165 offset:36864
	ds_read_b128 v[196:199], v165 offset:38912
	ds_read_b128 v[158:161], v165 offset:33792
	ds_read_b128 v[170:173], v165 offset:35840
	ds_read_b128 v[192:195], v165 offset:37888
	ds_read_b128 v[200:203], v165 offset:39936
	global_load_lds_dwordx4 v144, s[18:19]
	s_mov_b32 m0, s72
	s_nop 0
	global_load_lds_dwordx4 v146, s[18:19]
	s_waitcnt lgkmcnt(8)
	s_barrier
	s_waitcnt lgkmcnt(7)
	v_mfma_f32_16x16x32_bf16 v[124:127], v[128:131], v[154:157], v[124:127]
	v_mfma_f32_16x16x32_bf16 v[120:123], v[136:139], v[154:157], v[120:123]
	s_waitcnt lgkmcnt(6)
	v_mfma_f32_16x16x32_bf16 v[108:111], v[128:131], v[166:169], v[108:111]
	v_mfma_f32_16x16x32_bf16 v[104:107], v[136:139], v[166:169], v[104:107]
	s_waitcnt lgkmcnt(5)
	v_mfma_f32_16x16x32_bf16 v[92:95], v[128:131], v[188:191], v[92:95]
	v_mfma_f32_16x16x32_bf16 v[88:91], v[136:139], v[188:191], v[88:91]
	s_waitcnt lgkmcnt(4)
	v_mfma_f32_16x16x32_bf16 v[76:79], v[128:131], v[196:199], v[76:79]
	v_mfma_f32_16x16x32_bf16 v[72:75], v[136:139], v[196:199], v[72:75]
	s_waitcnt lgkmcnt(3)
	v_mfma_f32_16x16x32_bf16 v[124:127], v[132:135], v[158:161], v[124:127]
	v_mfma_f32_16x16x32_bf16 v[120:123], v[140:143], v[158:161], v[120:123]
	s_waitcnt lgkmcnt(2)
	v_mfma_f32_16x16x32_bf16 v[108:111], v[132:135], v[170:173], v[108:111]
	v_mfma_f32_16x16x32_bf16 v[104:107], v[140:143], v[170:173], v[104:107]
	s_waitcnt lgkmcnt(1)
	v_mfma_f32_16x16x32_bf16 v[92:95], v[132:135], v[192:195], v[92:95]
	v_mfma_f32_16x16x32_bf16 v[88:91], v[140:143], v[192:195], v[88:91]
	s_waitcnt lgkmcnt(0)
	v_mfma_f32_16x16x32_bf16 v[76:79], v[132:135], v[200:203], v[76:79]
	v_mfma_f32_16x16x32_bf16 v[72:75], v[140:143], v[200:203], v[72:75]
	s_barrier
	s_add_i32 s29, 0, 0x1c000
	s_add_i32 s18, s28, s68
	v_add_u32_e32 v232, s29, v164
	v_lshl_add_u64 v[174:175], v[174:175], 0, s[40:41]
	s_mov_b32 m0, s18
	ds_read_b128 v[204:207], v232
	ds_read_b128 v[208:211], v232 offset:1024
	ds_read_b128 v[212:215], v232 offset:2048
	ds_read_b128 v[232:235], v232 offset:3072
	global_load_lds_dwordx4 v[174:175], off
	v_lshl_add_u64 v[174:175], v[216:217], 0, s[40:41]
	s_add_i32 m0, s18, 0x2000
	s_nop 0
	global_load_lds_dwordx4 v[174:175], off
	s_barrier
	s_waitcnt lgkmcnt(3)
	v_mfma_f32_16x16x32_bf16 v[116:119], v[204:207], v[154:157], v[116:119]
	s_waitcnt lgkmcnt(1)
	v_mfma_f32_16x16x32_bf16 v[112:115], v[212:215], v[154:157], v[112:115]
	v_mfma_f32_16x16x32_bf16 v[100:103], v[204:207], v[166:169], v[100:103]
	v_mfma_f32_16x16x32_bf16 v[96:99], v[212:215], v[166:169], v[96:99]
	v_mfma_f32_16x16x32_bf16 v[84:87], v[204:207], v[188:191], v[84:87]
	v_mfma_f32_16x16x32_bf16 v[80:83], v[212:215], v[188:191], v[80:83]
	v_mfma_f32_16x16x32_bf16 v[68:71], v[204:207], v[196:199], v[68:71]
	v_mfma_f32_16x16x32_bf16 v[64:67], v[212:215], v[196:199], v[64:67]
	v_mfma_f32_16x16x32_bf16 v[116:119], v[208:211], v[158:161], v[116:119]
	s_waitcnt lgkmcnt(0)
	v_mfma_f32_16x16x32_bf16 v[112:115], v[232:235], v[158:161], v[112:115]
	v_mfma_f32_16x16x32_bf16 v[100:103], v[208:211], v[170:173], v[100:103]
	v_mfma_f32_16x16x32_bf16 v[96:99], v[232:235], v[170:173], v[96:99]
	v_mfma_f32_16x16x32_bf16 v[84:87], v[208:211], v[192:195], v[84:87]
	v_mfma_f32_16x16x32_bf16 v[80:83], v[232:235], v[192:195], v[80:83]
	v_mfma_f32_16x16x32_bf16 v[68:71], v[208:211], v[200:203], v[68:71]
	v_mfma_f32_16x16x32_bf16 v[64:67], v[232:235], v[200:203], v[64:67]
	s_mov_b32 m0, s75
	v_lshl_add_u64 v[174:175], v[236:237], 0, s[40:41]
	s_barrier
	ds_read_b128 v[154:157], v165 offset:49152
	ds_read_b128 v[166:169], v165 offset:51200
	ds_read_b128 v[188:191], v165 offset:53248
	ds_read_b128 v[196:199], v165 offset:55296
	ds_read_b128 v[158:161], v165 offset:50176
	ds_read_b128 v[170:173], v165 offset:52224
	ds_read_b128 v[192:195], v165 offset:54272
	ds_read_b128 v[200:203], v165 offset:56320
	global_load_lds_dwordx4 v[174:175], off
	v_lshl_add_u64 v[174:175], v[238:239], 0, s[40:41]
	s_mov_b32 m0, s76
	s_nop 0
	global_load_lds_dwordx4 v[174:175], off
	s_barrier
	s_waitcnt lgkmcnt(7)
	v_mfma_f32_16x16x32_bf16 v[60:63], v[128:131], v[154:157], v[60:63]
	v_mfma_f32_16x16x32_bf16 v[56:59], v[136:139], v[154:157], v[56:59]
	s_waitcnt lgkmcnt(6)
	v_mfma_f32_16x16x32_bf16 v[44:47], v[128:131], v[166:169], v[44:47]
	v_mfma_f32_16x16x32_bf16 v[40:43], v[136:139], v[166:169], v[40:43]
	s_waitcnt lgkmcnt(5)
	v_mfma_f32_16x16x32_bf16 v[28:31], v[128:131], v[188:191], v[28:31]
	v_mfma_f32_16x16x32_bf16 v[24:27], v[136:139], v[188:191], v[24:27]
	s_waitcnt lgkmcnt(4)
	v_mfma_f32_16x16x32_bf16 v[12:15], v[128:131], v[196:199], v[12:15]
	v_mfma_f32_16x16x32_bf16 v[8:11], v[136:139], v[196:199], v[8:11]
	s_waitcnt lgkmcnt(3)
	v_mfma_f32_16x16x32_bf16 v[60:63], v[132:135], v[158:161], v[60:63]
	v_mfma_f32_16x16x32_bf16 v[56:59], v[140:143], v[158:161], v[56:59]
	s_waitcnt lgkmcnt(2)
	v_mfma_f32_16x16x32_bf16 v[44:47], v[132:135], v[170:173], v[44:47]
	v_mfma_f32_16x16x32_bf16 v[40:43], v[140:143], v[170:173], v[40:43]
	s_waitcnt lgkmcnt(1)
	v_mfma_f32_16x16x32_bf16 v[28:31], v[132:135], v[192:195], v[28:31]
	v_mfma_f32_16x16x32_bf16 v[24:27], v[140:143], v[192:195], v[24:27]
	s_waitcnt lgkmcnt(0)
	v_mfma_f32_16x16x32_bf16 v[12:15], v[132:135], v[200:203], v[12:15]
	v_mfma_f32_16x16x32_bf16 v[8:11], v[140:143], v[200:203], v[8:11]
	s_barrier
	s_add_u32 s18, s62, 0x18080
	s_addc_u32 s19, s63, 0
	s_add_i32 s28, s29, s68
	s_mov_b32 m0, s28
	s_nop 0
	global_load_lds_dwordx4 v176, s[18:19]
	s_add_i32 m0, s28, 0x2000
	s_nop 0
	global_load_lds_dwordx4 v148, s[18:19]
	s_waitcnt vmcnt(6)
	s_barrier
	v_mfma_f32_16x16x32_bf16 v[52:55], v[204:207], v[154:157], v[52:55]
	v_mfma_f32_16x16x32_bf16 v[48:51], v[212:215], v[154:157], v[48:51]
	v_mfma_f32_16x16x32_bf16 v[36:39], v[204:207], v[166:169], v[36:39]
	v_mfma_f32_16x16x32_bf16 v[32:35], v[212:215], v[166:169], v[32:35]
	v_mfma_f32_16x16x32_bf16 v[20:23], v[204:207], v[188:191], v[20:23]
	v_mfma_f32_16x16x32_bf16 v[16:19], v[212:215], v[188:191], v[16:19]
	v_mfma_f32_16x16x32_bf16 v[4:7], v[204:207], v[196:199], v[4:7]
	v_mfma_f32_16x16x32_bf16 v[0:3], v[212:215], v[196:199], v[0:3]
	v_mfma_f32_16x16x32_bf16 v[52:55], v[208:211], v[158:161], v[52:55]
	v_mfma_f32_16x16x32_bf16 v[48:51], v[232:235], v[158:161], v[48:51]
	v_mfma_f32_16x16x32_bf16 v[36:39], v[208:211], v[170:173], v[36:39]
	v_mfma_f32_16x16x32_bf16 v[32:35], v[232:235], v[170:173], v[32:35]
	v_mfma_f32_16x16x32_bf16 v[20:23], v[208:211], v[192:195], v[20:23]
	v_mfma_f32_16x16x32_bf16 v[16:19], v[232:235], v[192:195], v[16:19]
	v_mfma_f32_16x16x32_bf16 v[4:7], v[208:211], v[200:203], v[4:7]
	v_mfma_f32_16x16x32_bf16 v[0:3], v[232:235], v[200:203], v[0:3]
	s_add_u32 s85, s85, 0x100
	s_addc_u32 s91, s91, 0
	s_cmp_lt_i32 vcc_lo, s67
	s_mov_b64 s[18:19], s[4:5]
	s_mov_b32 s62, vcc_lo
	s_barrier
	s_cbranch_scc1 .LBB0_413
	s_ashr_i32 s4, s66, 2
	v_mov_b32_e32 v128, v163
	v_mov_b32_e32 v166, v162
	s_cmp_eq_u32 s4, 2
	s_cbranch_scc1 .LBB0_416
	s_mul_i32 s13, s4, 0x2280000
	s_mul_hi_i32 s5, s4, 0x2280000
	s_add_u32 s18, s13, 0x5858000
	s_addc_u32 s19, s5, 0
	s_mov_b32 s62, 1.0
	s_branch .LBB0_417

.LBB0_505:
	s_add_u32 s6, s4, 0xfff80080
	s_addc_u32 s7, s5, -1
	s_add_i32 s28, 0, 0x10000
	v_add_u32_e32 v154, s28, v144
	ds_read_b128 v[138:141], v154
	ds_read_b128 v[146:149], v154 offset:1024
	ds_read_b128 v[150:153], v154 offset:2048
	ds_read_b128 v[154:157], v154 offset:3072
	s_cmp_eq_u32 s72, 28
	s_cselect_b32 s9, s10, s7
	s_cselect_b32 s8, s11, s6
	s_cselect_b32 s7, s63, s71
	s_cselect_b32 s6, s65, s70
	s_add_i32 m0, s17, 0xc000
	ds_read_b128 v[158:161], v145
	ds_read_b128 v[166:169], v145 offset:2048
	ds_read_b128 v[188:191], v145 offset:4096
	ds_read_b128 v[196:199], v145 offset:6144
	ds_read_b128 v[162:165], v145 offset:1024
	ds_read_b128 v[170:173], v145 offset:3072
	ds_read_b128 v[192:195], v145 offset:5120
	ds_read_b128 v[200:203], v145 offset:7168
	global_load_lds_dwordx4 v134, s[4:5]
	v_lshl_add_u64 v[174:175], s[4:5], 0, v[136:137]
	s_add_i32 m0, s17, 0xe000
	s_nop 0
	global_load_lds_dwordx4 v[174:175], off
	s_waitcnt lgkmcnt(8)
	s_barrier
	s_waitcnt lgkmcnt(7)
	v_mfma_f32_16x16x32_bf16 v[124:127], v[138:141], v[158:161], v[124:127]
	v_mfma_f32_16x16x32_bf16 v[120:123], v[150:153], v[158:161], v[120:123]
	s_waitcnt lgkmcnt(6)
	v_mfma_f32_16x16x32_bf16 v[116:119], v[138:141], v[166:169], v[116:119]
	v_mfma_f32_16x16x32_bf16 v[108:111], v[150:153], v[166:169], v[108:111]
	s_waitcnt lgkmcnt(5)
	v_mfma_f32_16x16x32_bf16 v[100:103], v[138:141], v[188:191], v[100:103]
	v_mfma_f32_16x16x32_bf16 v[92:95], v[150:153], v[188:191], v[92:95]
	s_waitcnt lgkmcnt(4)
	v_mfma_f32_16x16x32_bf16 v[84:87], v[138:141], v[196:199], v[84:87]
	v_mfma_f32_16x16x32_bf16 v[76:79], v[150:153], v[196:199], v[76:79]
	s_waitcnt lgkmcnt(3)
	v_mfma_f32_16x16x32_bf16 v[124:127], v[146:149], v[162:165], v[124:127]
	v_mfma_f32_16x16x32_bf16 v[120:123], v[154:157], v[162:165], v[120:123]
	s_waitcnt lgkmcnt(2)
	v_mfma_f32_16x16x32_bf16 v[116:119], v[146:149], v[170:173], v[116:119]
	v_mfma_f32_16x16x32_bf16 v[108:111], v[154:157], v[170:173], v[108:111]
	s_waitcnt lgkmcnt(1)
	v_mfma_f32_16x16x32_bf16 v[100:103], v[146:149], v[192:195], v[100:103]
	v_mfma_f32_16x16x32_bf16 v[92:95], v[154:157], v[192:195], v[92:95]
	s_waitcnt lgkmcnt(0)
	v_mfma_f32_16x16x32_bf16 v[84:87], v[146:149], v[200:203], v[84:87]
	v_mfma_f32_16x16x32_bf16 v[76:79], v[154:157], v[200:203], v[76:79]
	s_barrier
	s_add_i32 s29, 0, 0x14000
	v_add_u32_e32 v174, s29, v144
	s_add_i32 s28, s28, s77
	ds_read_b128 v[204:207], v174
	ds_read_b128 v[208:211], v174 offset:1024
	ds_read_b128 v[212:215], v174 offset:2048
	ds_read_b128 v[232:235], v174 offset:3072
	v_lshl_add_u64 v[174:175], s[6:7], 0, v[176:177]
	s_mov_b32 m0, s28
	v_lshl_add_u64 v[216:217], s[6:7], 0, v[132:133]
	global_load_lds_dwordx4 v[174:175], off
	s_add_i32 m0, s28, 0x2000
	s_nop 0
	global_load_lds_dwordx4 v[216:217], off
	s_barrier
	s_waitcnt lgkmcnt(3)
	v_mfma_f32_16x16x32_bf16 v[112:115], v[204:207], v[158:161], v[112:115]
	s_waitcnt lgkmcnt(1)
	v_mfma_f32_16x16x32_bf16 v[104:107], v[212:215], v[158:161], v[104:107]
	v_mfma_f32_16x16x32_bf16 v[96:99], v[204:207], v[166:169], v[96:99]
	v_mfma_f32_16x16x32_bf16 v[88:91], v[212:215], v[166:169], v[88:91]
	v_mfma_f32_16x16x32_bf16 v[80:83], v[204:207], v[188:191], v[80:83]
	v_mfma_f32_16x16x32_bf16 v[72:75], v[212:215], v[188:191], v[72:75]
	v_mfma_f32_16x16x32_bf16 v[68:71], v[204:207], v[196:199], v[68:71]
	v_mfma_f32_16x16x32_bf16 v[64:67], v[212:215], v[196:199], v[64:67]
	v_mfma_f32_16x16x32_bf16 v[112:115], v[208:211], v[162:165], v[112:115]
	s_waitcnt lgkmcnt(0)
	v_mfma_f32_16x16x32_bf16 v[104:107], v[232:235], v[162:165], v[104:107]
	v_mfma_f32_16x16x32_bf16 v[96:99], v[208:211], v[170:173], v[96:99]
	v_mfma_f32_16x16x32_bf16 v[88:91], v[232:235], v[170:173], v[88:91]
	v_mfma_f32_16x16x32_bf16 v[80:83], v[208:211], v[192:195], v[80:83]
	v_mfma_f32_16x16x32_bf16 v[72:75], v[232:235], v[192:195], v[72:75]
	v_mfma_f32_16x16x32_bf16 v[68:71], v[208:211], v[200:203], v[68:71]
	v_mfma_f32_16x16x32_bf16 v[64:67], v[232:235], v[200:203], v[64:67]
	s_mov_b32 m0, s17
	v_lshl_add_u64 v[236:237], s[8:9], 0, v[128:129]
	s_barrier
	ds_read_b128 v[158:161], v145 offset:16384
	ds_read_b128 v[166:169], v145 offset:18432
	ds_read_b128 v[188:191], v145 offset:20480
	ds_read_b128 v[196:199], v145 offset:22528
	ds_read_b128 v[162:165], v145 offset:17408
	ds_read_b128 v[170:173], v145 offset:19456
	ds_read_b128 v[192:195], v145 offset:21504
	ds_read_b128 v[200:203], v145 offset:23552
	global_load_lds_dwordx4 v[236:237], off
	v_lshl_add_u64 v[238:239], s[8:9], 0, v[130:131]
	s_mov_b32 m0, s19
	s_nop 0
	global_load_lds_dwordx4 v[238:239], off
	s_barrier
	s_waitcnt lgkmcnt(7)
	v_mfma_f32_16x16x32_bf16 v[60:63], v[138:141], v[158:161], v[60:63]
	v_mfma_f32_16x16x32_bf16 v[56:59], v[150:153], v[158:161], v[56:59]
	s_waitcnt lgkmcnt(6)
	v_mfma_f32_16x16x32_bf16 v[52:55], v[138:141], v[166:169], v[52:55]
	v_mfma_f32_16x16x32_bf16 v[44:47], v[150:153], v[166:169], v[44:47]
	s_waitcnt lgkmcnt(5)
	v_mfma_f32_16x16x32_bf16 v[36:39], v[138:141], v[188:191], v[36:39]
	v_mfma_f32_16x16x32_bf16 v[28:31], v[150:153], v[188:191], v[28:31]
	s_waitcnt lgkmcnt(4)
	v_mfma_f32_16x16x32_bf16 v[20:23], v[138:141], v[196:199], v[20:23]
	v_mfma_f32_16x16x32_bf16 v[12:15], v[150:153], v[196:199], v[12:15]
	s_waitcnt lgkmcnt(3)
	v_mfma_f32_16x16x32_bf16 v[60:63], v[146:149], v[162:165], v[60:63]
	v_mfma_f32_16x16x32_bf16 v[56:59], v[154:157], v[162:165], v[56:59]
	s_waitcnt lgkmcnt(2)
	v_mfma_f32_16x16x32_bf16 v[52:55], v[146:149], v[170:173], v[52:55]
	v_mfma_f32_16x16x32_bf16 v[44:47], v[154:157], v[170:173], v[44:47]
	s_waitcnt lgkmcnt(1)
	v_mfma_f32_16x16x32_bf16 v[36:39], v[146:149], v[192:195], v[36:39]
	v_mfma_f32_16x16x32_bf16 v[28:31], v[154:157], v[192:195], v[28:31]
	s_waitcnt lgkmcnt(0)
	v_mfma_f32_16x16x32_bf16 v[20:23], v[146:149], v[200:203], v[20:23]
	v_mfma_f32_16x16x32_bf16 v[12:15], v[154:157], v[200:203], v[12:15]
	s_barrier
	s_add_u32 vcc_lo, s6, 0x80000
	s_addc_u32 vcc_hi, s7, 0
	s_add_i32 s28, s29, s77
	v_lshl_add_u64 v[138:139], vcc, 0, v[176:177]
	s_mov_b32 m0, s28
	s_nop 0
	global_load_lds_dwordx4 v[138:139], off
	v_lshl_add_u64 v[138:139], vcc, 0, v[132:133]
	s_add_i32 m0, s28, 0x2000
	s_nop 0
	global_load_lds_dwordx4 v[138:139], off
	s_waitcnt vmcnt(6)
	s_barrier
	v_mfma_f32_16x16x32_bf16 v[48:51], v[204:207], v[158:161], v[48:51]
	v_mfma_f32_16x16x32_bf16 v[40:43], v[212:215], v[158:161], v[40:43]
	v_mfma_f32_16x16x32_bf16 v[32:35], v[204:207], v[166:169], v[32:35]
	v_mfma_f32_16x16x32_bf16 v[24:27], v[212:215], v[166:169], v[24:27]
	v_mfma_f32_16x16x32_bf16 v[16:19], v[204:207], v[188:191], v[16:19]
	v_mfma_f32_16x16x32_bf16 v[8:11], v[212:215], v[188:191], v[8:11]
	v_mfma_f32_16x16x32_bf16 v[4:7], v[204:207], v[196:199], v[4:7]
	v_mfma_f32_16x16x32_bf16 v[0:3], v[212:215], v[196:199], v[0:3]
	v_mfma_f32_16x16x32_bf16 v[48:51], v[208:211], v[162:165], v[48:51]
	v_mfma_f32_16x16x32_bf16 v[40:43], v[232:235], v[162:165], v[40:43]
	v_mfma_f32_16x16x32_bf16 v[32:35], v[208:211], v[170:173], v[32:35]
	v_mfma_f32_16x16x32_bf16 v[24:27], v[232:235], v[170:173], v[24:27]
	v_mfma_f32_16x16x32_bf16 v[16:19], v[208:211], v[192:195], v[16:19]
	v_mfma_f32_16x16x32_bf16 v[8:11], v[232:235], v[192:195], v[8:11]
	v_mfma_f32_16x16x32_bf16 v[4:7], v[208:211], v[200:203], v[4:7]
	v_mfma_f32_16x16x32_bf16 v[0:3], v[232:235], v[200:203], v[0:3]
	s_add_i32 s28, 0, 0x18000
	v_add_u32_e32 v154, s28, v144
	s_barrier
	ds_read_b128 v[138:141], v154
	ds_read_b128 v[146:149], v154 offset:1024
	ds_read_b128 v[150:153], v154 offset:2048
	ds_read_b128 v[154:157], v154 offset:3072
	s_add_u32 s8, s8, 0x80000
	s_addc_u32 s9, s9, 0
	s_mov_b32 m0, s78
	ds_read_b128 v[158:161], v145 offset:32768
	ds_read_b128 v[166:169], v145 offset:34816
	ds_read_b128 v[188:191], v145 offset:36864
	ds_read_b128 v[196:199], v145 offset:38912
	ds_read_b128 v[162:165], v145 offset:33792
	ds_read_b128 v[170:173], v145 offset:35840
	ds_read_b128 v[192:195], v145 offset:37888
	ds_read_b128 v[200:203], v145 offset:39936
	global_load_lds_dwordx4 v128, s[8:9]
	s_mov_b32 m0, s79
	s_nop 0
	global_load_lds_dwordx4 v130, s[8:9]
	s_waitcnt lgkmcnt(8)
	s_barrier
	s_waitcnt lgkmcnt(7)
	v_mfma_f32_16x16x32_bf16 v[124:127], v[138:141], v[158:161], v[124:127]
	v_mfma_f32_16x16x32_bf16 v[120:123], v[150:153], v[158:161], v[120:123]
	s_waitcnt lgkmcnt(6)
	v_mfma_f32_16x16x32_bf16 v[116:119], v[138:141], v[166:169], v[116:119]
	v_mfma_f32_16x16x32_bf16 v[108:111], v[150:153], v[166:169], v[108:111]
	s_waitcnt lgkmcnt(5)
	v_mfma_f32_16x16x32_bf16 v[100:103], v[138:141], v[188:191], v[100:103]
	v_mfma_f32_16x16x32_bf16 v[92:95], v[150:153], v[188:191], v[92:95]
	s_waitcnt lgkmcnt(4)
	v_mfma_f32_16x16x32_bf16 v[84:87], v[138:141], v[196:199], v[84:87]
	v_mfma_f32_16x16x32_bf16 v[76:79], v[150:153], v[196:199], v[76:79]
	s_waitcnt lgkmcnt(3)
	v_mfma_f32_16x16x32_bf16 v[124:127], v[146:149], v[162:165], v[124:127]
	v_mfma_f32_16x16x32_bf16 v[120:123], v[154:157], v[162:165], v[120:123]
	s_waitcnt lgkmcnt(2)
	v_mfma_f32_16x16x32_bf16 v[116:119], v[146:149], v[170:173], v[116:119]
	v_mfma_f32_16x16x32_bf16 v[108:111], v[154:157], v[170:173], v[108:111]
	s_waitcnt lgkmcnt(1)
	v_mfma_f32_16x16x32_bf16 v[100:103], v[146:149], v[192:195], v[100:103]
	v_mfma_f32_16x16x32_bf16 v[92:95], v[154:157], v[192:195], v[92:95]
	s_waitcnt lgkmcnt(0)
	v_mfma_f32_16x16x32_bf16 v[84:87], v[146:149], v[200:203], v[84:87]
	v_mfma_f32_16x16x32_bf16 v[76:79], v[154:157], v[200:203], v[76:79]
	s_barrier
	s_add_i32 s8, 0, 0x1c000
	s_add_i32 s9, s28, s77
	v_add_u32_e32 v232, s8, v144
	v_lshl_add_u64 v[174:175], v[174:175], 0, s[40:41]
	s_mov_b32 m0, s9
	ds_read_b128 v[204:207], v232
	ds_read_b128 v[208:211], v232 offset:1024
	ds_read_b128 v[212:215], v232 offset:2048
	ds_read_b128 v[232:235], v232 offset:3072
	global_load_lds_dwordx4 v[174:175], off
	v_lshl_add_u64 v[174:175], v[216:217], 0, s[40:41]
	s_add_i32 m0, s9, 0x2000
	s_nop 0
	global_load_lds_dwordx4 v[174:175], off
	s_barrier
	s_waitcnt lgkmcnt(3)
	v_mfma_f32_16x16x32_bf16 v[112:115], v[204:207], v[158:161], v[112:115]
	s_waitcnt lgkmcnt(1)
	v_mfma_f32_16x16x32_bf16 v[104:107], v[212:215], v[158:161], v[104:107]
	v_mfma_f32_16x16x32_bf16 v[96:99], v[204:207], v[166:169], v[96:99]
	v_mfma_f32_16x16x32_bf16 v[88:91], v[212:215], v[166:169], v[88:91]
	v_mfma_f32_16x16x32_bf16 v[80:83], v[204:207], v[188:191], v[80:83]
	v_mfma_f32_16x16x32_bf16 v[72:75], v[212:215], v[188:191], v[72:75]
	v_mfma_f32_16x16x32_bf16 v[68:71], v[204:207], v[196:199], v[68:71]
	v_mfma_f32_16x16x32_bf16 v[64:67], v[212:215], v[196:199], v[64:67]
	v_mfma_f32_16x16x32_bf16 v[112:115], v[208:211], v[162:165], v[112:115]
	s_waitcnt lgkmcnt(0)
	v_mfma_f32_16x16x32_bf16 v[104:107], v[232:235], v[162:165], v[104:107]
	v_mfma_f32_16x16x32_bf16 v[96:99], v[208:211], v[170:173], v[96:99]
	v_mfma_f32_16x16x32_bf16 v[88:91], v[232:235], v[170:173], v[88:91]
	v_mfma_f32_16x16x32_bf16 v[80:83], v[208:211], v[192:195], v[80:83]
	v_mfma_f32_16x16x32_bf16 v[72:75], v[232:235], v[192:195], v[72:75]
	v_mfma_f32_16x16x32_bf16 v[68:71], v[208:211], v[200:203], v[68:71]
	v_mfma_f32_16x16x32_bf16 v[64:67], v[232:235], v[200:203], v[64:67]
	s_mov_b32 m0, s82
	v_lshl_add_u64 v[174:175], v[236:237], 0, s[40:41]
	s_barrier
	ds_read_b128 v[158:161], v145 offset:49152
	ds_read_b128 v[166:169], v145 offset:51200
	ds_read_b128 v[188:191], v145 offset:53248
	ds_read_b128 v[196:199], v145 offset:55296
	ds_read_b128 v[162:165], v145 offset:50176
	ds_read_b128 v[170:173], v145 offset:52224
	ds_read_b128 v[192:195], v145 offset:54272
	ds_read_b128 v[200:203], v145 offset:56320
	global_load_lds_dwordx4 v[174:175], off
	v_lshl_add_u64 v[174:175], v[238:239], 0, s[40:41]
	s_mov_b32 m0, s83
	s_nop 0
	global_load_lds_dwordx4 v[174:175], off
	s_barrier
	s_waitcnt lgkmcnt(7)
	v_mfma_f32_16x16x32_bf16 v[60:63], v[138:141], v[158:161], v[60:63]
	v_mfma_f32_16x16x32_bf16 v[56:59], v[150:153], v[158:161], v[56:59]
	s_waitcnt lgkmcnt(6)
	v_mfma_f32_16x16x32_bf16 v[52:55], v[138:141], v[166:169], v[52:55]
	v_mfma_f32_16x16x32_bf16 v[44:47], v[150:153], v[166:169], v[44:47]
	s_waitcnt lgkmcnt(5)
	v_mfma_f32_16x16x32_bf16 v[36:39], v[138:141], v[188:191], v[36:39]
	v_mfma_f32_16x16x32_bf16 v[28:31], v[150:153], v[188:191], v[28:31]
	s_waitcnt lgkmcnt(4)
	v_mfma_f32_16x16x32_bf16 v[20:23], v[138:141], v[196:199], v[20:23]
	v_mfma_f32_16x16x32_bf16 v[12:15], v[150:153], v[196:199], v[12:15]
	s_waitcnt lgkmcnt(3)
	v_mfma_f32_16x16x32_bf16 v[60:63], v[146:149], v[162:165], v[60:63]
	v_mfma_f32_16x16x32_bf16 v[56:59], v[154:157], v[162:165], v[56:59]
	s_waitcnt lgkmcnt(2)
	v_mfma_f32_16x16x32_bf16 v[52:55], v[146:149], v[170:173], v[52:55]
	v_mfma_f32_16x16x32_bf16 v[44:47], v[154:157], v[170:173], v[44:47]
	s_waitcnt lgkmcnt(1)
	v_mfma_f32_16x16x32_bf16 v[36:39], v[146:149], v[192:195], v[36:39]
	v_mfma_f32_16x16x32_bf16 v[28:31], v[154:157], v[192:195], v[28:31]
	s_waitcnt lgkmcnt(0)
	v_mfma_f32_16x16x32_bf16 v[20:23], v[146:149], v[200:203], v[20:23]
	v_mfma_f32_16x16x32_bf16 v[12:15], v[154:157], v[200:203], v[12:15]
	s_barrier
	s_add_u32 s6, s6, 0x80080
	s_addc_u32 s7, s7, 0
	s_add_i32 s8, s8, s77
	s_mov_b32 m0, s8
	s_nop 0
	global_load_lds_dwordx4 v176, s[6:7]
	s_add_i32 m0, s8, 0x2000
	s_nop 0
	global_load_lds_dwordx4 v132, s[6:7]
	s_waitcnt vmcnt(6)
	s_barrier
	v_mfma_f32_16x16x32_bf16 v[48:51], v[204:207], v[158:161], v[48:51]
	v_mfma_f32_16x16x32_bf16 v[40:43], v[212:215], v[158:161], v[40:43]
	v_mfma_f32_16x16x32_bf16 v[32:35], v[204:207], v[166:169], v[32:35]
	v_mfma_f32_16x16x32_bf16 v[24:27], v[212:215], v[166:169], v[24:27]
	v_mfma_f32_16x16x32_bf16 v[16:19], v[204:207], v[188:191], v[16:19]
	v_mfma_f32_16x16x32_bf16 v[8:11], v[212:215], v[188:191], v[8:11]
	v_mfma_f32_16x16x32_bf16 v[4:7], v[204:207], v[196:199], v[4:7]
	v_mfma_f32_16x16x32_bf16 v[0:3], v[212:215], v[196:199], v[0:3]
	v_mfma_f32_16x16x32_bf16 v[48:51], v[208:211], v[162:165], v[48:51]
	v_mfma_f32_16x16x32_bf16 v[40:43], v[232:235], v[162:165], v[40:43]
	v_mfma_f32_16x16x32_bf16 v[32:35], v[208:211], v[170:173], v[32:35]
	v_mfma_f32_16x16x32_bf16 v[24:27], v[232:235], v[170:173], v[24:27]
	v_mfma_f32_16x16x32_bf16 v[16:19], v[208:211], v[192:195], v[16:19]
	v_mfma_f32_16x16x32_bf16 v[8:11], v[232:235], v[192:195], v[8:11]
	v_mfma_f32_16x16x32_bf16 v[4:7], v[208:211], v[200:203], v[4:7]
	v_mfma_f32_16x16x32_bf16 v[0:3], v[232:235], v[200:203], v[0:3]
	s_add_i32 s72, s72, 2
	s_add_u32 s4, s4, 0x100
	s_addc_u32 s5, s5, 0
	s_add_u32 s70, s70, 0x100
	s_addc_u32 s71, s71, 0
	s_cmp_lt_u32 s72, 30
	s_barrier
	s_cbranch_scc1 .LBB0_505
	v_mov_b32_e32 v147, v142
	v_mov_b32_e32 v146, v143
	s_cmp_lt_i32 s16, 12
	s_mov_b64 s[4:5], -1
	s_cbranch_scc1 .LBB0_1052
	s_lshl_b32 s4, s18, 8
	s_add_i32 s4, s4, s80
	v_add_u32_e32 v149, s4, v147
	s_lshl_b32 s4, s16, 8
	s_add_i32 s4, s84, s4
	v_lshl_add_u32 v138, v146, 3, s4
	v_mad_i64_i32 v[140:141], s[4:5], v149, s97, 0
	v_cmp_gt_i32_e32 vcc, s34, v138
	s_and_saveexec_b64 s[10:11], vcc
	s_cbranch_execz .LBB0_541
	v_cmp_lt_i32_e64 s[8:9], 63, v138
	v_cmp_gt_u32_e64 s[4:5], s93, v138
	v_cmp_gt_u32_e64 s[6:7], s96, v138
	s_and_saveexec_b64 s[70:71], s[8:9]
	s_xor_b64 s[70:71], exec, s[70:71]
	s_cbranch_execz .LBB0_510
	v_mul_f32_e32 v139, 0xbfb8aa3b, v124
	v_exp_f32_e32 v139, v139
	s_nop 0
	v_add_f32_e32 v139, 1.0, v139
	v_rcp_f32_e32 v139, v139
	s_nop 0
	v_cndmask_b32_e64 v139, 0, v139, s[6:7]
	v_cndmask_b32_e64 v139, v139, v124, s[4:5]
	s_andn2_saveexec_b64 s[70:71], s[70:71]
	s_cbranch_execz .LBB0_512
	s_branch .LBB0_511

.LBB0_1114:
	s_add_i32 vcc_hi, s66, 2
	s_add_u32 s28, s64, 0x80
	s_addc_u32 s29, s65, 0
	s_add_i32 s88, 0, 0x10000
	v_add_u32_e32 v140, s88, v194
	ds_read_b128 v[128:131], v140
	ds_read_b128 v[132:135], v140 offset:1024
	ds_read_b128 v[136:139], v140 offset:2048
	ds_read_b128 v[140:143], v140 offset:3072
	s_cmp_eq_u32 s85, s66
	s_cselect_b32 s66, s4, s28
	s_cselect_b32 s67, s5, s29
	s_cselect_b32 s69, s7, vcc_lo
	s_cselect_b32 s68, s6, s91
	s_add_i32 m0, s70, 0xc000
	ds_read_b128 v[144:147], v195
	ds_read_b128 v[162:165], v195 offset:2048
	ds_read_b128 v[170:173], v195 offset:4096
	ds_read_b128 v[196:199], v195 offset:6144
	ds_read_b128 v[148:151], v195 offset:1024
	ds_read_b128 v[166:169], v195 offset:3072
	ds_read_b128 v[188:191], v195 offset:5120
	ds_read_b128 v[200:203], v195 offset:7168
	global_load_lds_dwordx4 v158, s[64:65]
	v_lshl_add_u64 v[174:175], s[64:65], 0, v[160:161]
	s_add_i32 m0, s70, 0xe000
	s_nop 0
	global_load_lds_dwordx4 v[174:175], off
	s_waitcnt lgkmcnt(8)
	s_barrier
	s_waitcnt lgkmcnt(7)
	v_mfma_f32_16x16x32_bf16 v[124:127], v[128:131], v[144:147], v[124:127]
	v_mfma_f32_16x16x32_bf16 v[120:123], v[136:139], v[144:147], v[120:123]
	s_waitcnt lgkmcnt(6)
	v_mfma_f32_16x16x32_bf16 v[108:111], v[128:131], v[162:165], v[108:111]
	v_mfma_f32_16x16x32_bf16 v[104:107], v[136:139], v[162:165], v[104:107]
	s_waitcnt lgkmcnt(5)
	v_mfma_f32_16x16x32_bf16 v[92:95], v[128:131], v[170:173], v[92:95]
	v_mfma_f32_16x16x32_bf16 v[88:91], v[136:139], v[170:173], v[88:91]
	s_waitcnt lgkmcnt(4)
	v_mfma_f32_16x16x32_bf16 v[76:79], v[128:131], v[196:199], v[76:79]
	v_mfma_f32_16x16x32_bf16 v[72:75], v[136:139], v[196:199], v[72:75]
	s_waitcnt lgkmcnt(3)
	v_mfma_f32_16x16x32_bf16 v[124:127], v[132:135], v[148:151], v[124:127]
	v_mfma_f32_16x16x32_bf16 v[120:123], v[140:143], v[148:151], v[120:123]
	s_waitcnt lgkmcnt(2)
	v_mfma_f32_16x16x32_bf16 v[108:111], v[132:135], v[166:169], v[108:111]
	v_mfma_f32_16x16x32_bf16 v[104:107], v[140:143], v[166:169], v[104:107]
	s_waitcnt lgkmcnt(1)
	v_mfma_f32_16x16x32_bf16 v[92:95], v[132:135], v[188:191], v[92:95]
	v_mfma_f32_16x16x32_bf16 v[88:91], v[140:143], v[188:191], v[88:91]
	s_waitcnt lgkmcnt(0)
	v_mfma_f32_16x16x32_bf16 v[76:79], v[132:135], v[200:203], v[76:79]
	v_mfma_f32_16x16x32_bf16 v[72:75], v[140:143], v[200:203], v[72:75]
	s_barrier
	s_add_i32 s28, 0, 0x14000
	v_add_u32_e32 v174, s28, v194
	s_add_i32 s29, s88, s47
	ds_read_b128 v[204:207], v174
	ds_read_b128 v[208:211], v174 offset:1024
	ds_read_b128 v[212:215], v174 offset:2048
	ds_read_b128 v[232:235], v174 offset:3072
	v_lshl_add_u64 v[174:175], s[68:69], 0, v[176:177]
	s_mov_b32 m0, s29
	v_lshl_add_u64 v[216:217], s[68:69], 0, v[156:157]
	global_load_lds_dwordx4 v[174:175], off
	s_add_i32 m0, s29, 0x2000
	s_nop 0
	global_load_lds_dwordx4 v[216:217], off
	s_barrier
	s_waitcnt lgkmcnt(3)
	v_mfma_f32_16x16x32_bf16 v[116:119], v[204:207], v[144:147], v[116:119]
	s_waitcnt lgkmcnt(1)
	v_mfma_f32_16x16x32_bf16 v[112:115], v[212:215], v[144:147], v[112:115]
	v_mfma_f32_16x16x32_bf16 v[100:103], v[204:207], v[162:165], v[100:103]
	v_mfma_f32_16x16x32_bf16 v[96:99], v[212:215], v[162:165], v[96:99]
	v_mfma_f32_16x16x32_bf16 v[84:87], v[204:207], v[170:173], v[84:87]
	v_mfma_f32_16x16x32_bf16 v[80:83], v[212:215], v[170:173], v[80:83]
	v_mfma_f32_16x16x32_bf16 v[68:71], v[204:207], v[196:199], v[68:71]
	v_mfma_f32_16x16x32_bf16 v[64:67], v[212:215], v[196:199], v[64:67]
	v_mfma_f32_16x16x32_bf16 v[116:119], v[208:211], v[148:151], v[116:119]
	s_waitcnt lgkmcnt(0)
	v_mfma_f32_16x16x32_bf16 v[112:115], v[232:235], v[148:151], v[112:115]
	v_mfma_f32_16x16x32_bf16 v[100:103], v[208:211], v[166:169], v[100:103]
	v_mfma_f32_16x16x32_bf16 v[96:99], v[232:235], v[166:169], v[96:99]
	v_mfma_f32_16x16x32_bf16 v[84:87], v[208:211], v[188:191], v[84:87]
	v_mfma_f32_16x16x32_bf16 v[80:83], v[232:235], v[188:191], v[80:83]
	v_mfma_f32_16x16x32_bf16 v[68:71], v[208:211], v[200:203], v[68:71]
	v_mfma_f32_16x16x32_bf16 v[64:67], v[232:235], v[200:203], v[64:67]
	s_mov_b32 m0, s70
	v_lshl_add_u64 v[236:237], s[66:67], 0, v[152:153]
	s_barrier
	ds_read_b128 v[144:147], v195 offset:16384
	ds_read_b128 v[162:165], v195 offset:18432
	ds_read_b128 v[170:173], v195 offset:20480
	ds_read_b128 v[196:199], v195 offset:22528
	ds_read_b128 v[148:151], v195 offset:17408
	ds_read_b128 v[166:169], v195 offset:19456
	ds_read_b128 v[188:191], v195 offset:21504
	ds_read_b128 v[200:203], v195 offset:23552
	global_load_lds_dwordx4 v[236:237], off
	v_lshl_add_u64 v[238:239], s[66:67], 0, v[154:155]
	s_mov_b32 m0, s71
	s_nop 0
	global_load_lds_dwordx4 v[238:239], off
	s_barrier
	s_waitcnt lgkmcnt(7)
	v_mfma_f32_16x16x32_bf16 v[60:63], v[128:131], v[144:147], v[60:63]
	v_mfma_f32_16x16x32_bf16 v[56:59], v[136:139], v[144:147], v[56:59]
	s_waitcnt lgkmcnt(6)
	v_mfma_f32_16x16x32_bf16 v[44:47], v[128:131], v[162:165], v[44:47]
	v_mfma_f32_16x16x32_bf16 v[40:43], v[136:139], v[162:165], v[40:43]
	s_waitcnt lgkmcnt(5)
	v_mfma_f32_16x16x32_bf16 v[28:31], v[128:131], v[170:173], v[28:31]
	v_mfma_f32_16x16x32_bf16 v[24:27], v[136:139], v[170:173], v[24:27]
	s_waitcnt lgkmcnt(4)
	v_mfma_f32_16x16x32_bf16 v[12:15], v[128:131], v[196:199], v[12:15]
	v_mfma_f32_16x16x32_bf16 v[8:11], v[136:139], v[196:199], v[8:11]
	s_waitcnt lgkmcnt(3)
	v_mfma_f32_16x16x32_bf16 v[60:63], v[132:135], v[148:151], v[60:63]
	v_mfma_f32_16x16x32_bf16 v[56:59], v[140:143], v[148:151], v[56:59]
	s_waitcnt lgkmcnt(2)
	v_mfma_f32_16x16x32_bf16 v[44:47], v[132:135], v[166:169], v[44:47]
	v_mfma_f32_16x16x32_bf16 v[40:43], v[140:143], v[166:169], v[40:43]
	s_waitcnt lgkmcnt(1)
	v_mfma_f32_16x16x32_bf16 v[28:31], v[132:135], v[188:191], v[28:31]
	v_mfma_f32_16x16x32_bf16 v[24:27], v[140:143], v[188:191], v[24:27]
	s_waitcnt lgkmcnt(0)
	v_mfma_f32_16x16x32_bf16 v[12:15], v[132:135], v[200:203], v[12:15]
	v_mfma_f32_16x16x32_bf16 v[8:11], v[140:143], v[200:203], v[8:11]
	s_barrier
	s_add_u32 s68, s68, s58
	s_addc_u32 s69, s69, 0
	s_add_i32 s28, s28, s47
	v_lshl_add_u64 v[240:241], s[68:69], 0, v[176:177]
	s_mov_b32 m0, s28
	v_lshl_add_u64 v[242:243], s[68:69], 0, v[156:157]
	global_load_lds_dwordx4 v[240:241], off
	s_add_i32 m0, s28, 0x2000
	s_nop 0
	global_load_lds_dwordx4 v[242:243], off
	s_waitcnt vmcnt(6)
	s_barrier
	v_mfma_f32_16x16x32_bf16 v[52:55], v[204:207], v[144:147], v[52:55]
	v_mfma_f32_16x16x32_bf16 v[48:51], v[212:215], v[144:147], v[48:51]
	v_mfma_f32_16x16x32_bf16 v[36:39], v[204:207], v[162:165], v[36:39]
	v_mfma_f32_16x16x32_bf16 v[32:35], v[212:215], v[162:165], v[32:35]
	v_mfma_f32_16x16x32_bf16 v[20:23], v[204:207], v[170:173], v[20:23]
	v_mfma_f32_16x16x32_bf16 v[16:19], v[212:215], v[170:173], v[16:19]
	v_mfma_f32_16x16x32_bf16 v[4:7], v[204:207], v[196:199], v[4:7]
	v_mfma_f32_16x16x32_bf16 v[0:3], v[212:215], v[196:199], v[0:3]
	v_mfma_f32_16x16x32_bf16 v[52:55], v[208:211], v[148:151], v[52:55]
	v_mfma_f32_16x16x32_bf16 v[48:51], v[232:235], v[148:151], v[48:51]
	v_mfma_f32_16x16x32_bf16 v[36:39], v[208:211], v[166:169], v[36:39]
	v_mfma_f32_16x16x32_bf16 v[32:35], v[232:235], v[166:169], v[32:35]
	v_mfma_f32_16x16x32_bf16 v[20:23], v[208:211], v[188:191], v[20:23]
	v_mfma_f32_16x16x32_bf16 v[16:19], v[232:235], v[188:191], v[16:19]
	v_mfma_f32_16x16x32_bf16 v[4:7], v[208:211], v[200:203], v[4:7]
	v_mfma_f32_16x16x32_bf16 v[0:3], v[232:235], v[200:203], v[0:3]
	s_add_i32 s28, 0, 0x18000
	v_add_u32_e32 v140, s28, v194
	s_barrier
	ds_read_b128 v[128:131], v140
	ds_read_b128 v[132:135], v140 offset:1024
	ds_read_b128 v[136:139], v140 offset:2048
	ds_read_b128 v[140:143], v140 offset:3072
	s_add_u32 s66, s66, s58
	s_addc_u32 s67, s67, 0
	s_mov_b32 m0, s72
	ds_read_b128 v[144:147], v195 offset:32768
	ds_read_b128 v[162:165], v195 offset:34816
	ds_read_b128 v[170:173], v195 offset:36864
	ds_read_b128 v[196:199], v195 offset:38912
	ds_read_b128 v[148:151], v195 offset:33792
	ds_read_b128 v[166:169], v195 offset:35840
	ds_read_b128 v[188:191], v195 offset:37888
	ds_read_b128 v[200:203], v195 offset:39936
	global_load_lds_dwordx4 v152, s[66:67]
	s_mov_b32 m0, s73
	s_nop 0
	global_load_lds_dwordx4 v154, s[66:67]
	s_waitcnt lgkmcnt(8)
	s_barrier
	s_waitcnt lgkmcnt(7)
	v_mfma_f32_16x16x32_bf16 v[124:127], v[128:131], v[144:147], v[124:127]
	v_mfma_f32_16x16x32_bf16 v[120:123], v[136:139], v[144:147], v[120:123]
	s_waitcnt lgkmcnt(6)
	v_mfma_f32_16x16x32_bf16 v[108:111], v[128:131], v[162:165], v[108:111]
	v_mfma_f32_16x16x32_bf16 v[104:107], v[136:139], v[162:165], v[104:107]
	s_waitcnt lgkmcnt(5)
	v_mfma_f32_16x16x32_bf16 v[92:95], v[128:131], v[170:173], v[92:95]
	v_mfma_f32_16x16x32_bf16 v[88:91], v[136:139], v[170:173], v[88:91]
	s_waitcnt lgkmcnt(4)
	v_mfma_f32_16x16x32_bf16 v[76:79], v[128:131], v[196:199], v[76:79]
	v_mfma_f32_16x16x32_bf16 v[72:75], v[136:139], v[196:199], v[72:75]
	s_waitcnt lgkmcnt(3)
	v_mfma_f32_16x16x32_bf16 v[124:127], v[132:135], v[148:151], v[124:127]
	v_mfma_f32_16x16x32_bf16 v[120:123], v[140:143], v[148:151], v[120:123]
	s_waitcnt lgkmcnt(2)
	v_mfma_f32_16x16x32_bf16 v[108:111], v[132:135], v[166:169], v[108:111]
	v_mfma_f32_16x16x32_bf16 v[104:107], v[140:143], v[166:169], v[104:107]
	s_waitcnt lgkmcnt(1)
	v_mfma_f32_16x16x32_bf16 v[92:95], v[132:135], v[188:191], v[92:95]
	v_mfma_f32_16x16x32_bf16 v[88:91], v[140:143], v[188:191], v[88:91]
	s_waitcnt lgkmcnt(0)
	v_mfma_f32_16x16x32_bf16 v[76:79], v[132:135], v[200:203], v[76:79]
	v_mfma_f32_16x16x32_bf16 v[72:75], v[140:143], v[200:203], v[72:75]
	s_barrier
	s_add_i32 s29, 0, 0x1c000
	s_add_i32 s28, s28, s47
	v_add_u32_e32 v232, s29, v194
	v_lshl_add_u64 v[174:175], v[174:175], 0, s[40:41]
	s_mov_b32 m0, s28
	ds_read_b128 v[204:207], v232
	ds_read_b128 v[208:211], v232 offset:1024
	ds_read_b128 v[212:215], v232 offset:2048
	ds_read_b128 v[232:235], v232 offset:3072
	global_load_lds_dwordx4 v[174:175], off
	v_lshl_add_u64 v[174:175], v[216:217], 0, s[40:41]
	s_add_i32 m0, s28, 0x2000
	s_nop 0
	global_load_lds_dwordx4 v[174:175], off
	s_barrier
	s_waitcnt lgkmcnt(3)
	v_mfma_f32_16x16x32_bf16 v[116:119], v[204:207], v[144:147], v[116:119]
	s_waitcnt lgkmcnt(1)
	v_mfma_f32_16x16x32_bf16 v[112:115], v[212:215], v[144:147], v[112:115]
	v_mfma_f32_16x16x32_bf16 v[100:103], v[204:207], v[162:165], v[100:103]
	v_mfma_f32_16x16x32_bf16 v[96:99], v[212:215], v[162:165], v[96:99]
	v_mfma_f32_16x16x32_bf16 v[84:87], v[204:207], v[170:173], v[84:87]
	v_mfma_f32_16x16x32_bf16 v[80:83], v[212:215], v[170:173], v[80:83]
	v_mfma_f32_16x16x32_bf16 v[68:71], v[204:207], v[196:199], v[68:71]
	v_mfma_f32_16x16x32_bf16 v[64:67], v[212:215], v[196:199], v[64:67]
	v_mfma_f32_16x16x32_bf16 v[116:119], v[208:211], v[148:151], v[116:119]
	s_waitcnt lgkmcnt(0)
	v_mfma_f32_16x16x32_bf16 v[112:115], v[232:235], v[148:151], v[112:115]
	v_mfma_f32_16x16x32_bf16 v[100:103], v[208:211], v[166:169], v[100:103]
	v_mfma_f32_16x16x32_bf16 v[96:99], v[232:235], v[166:169], v[96:99]
	v_mfma_f32_16x16x32_bf16 v[84:87], v[208:211], v[188:191], v[84:87]
	v_mfma_f32_16x16x32_bf16 v[80:83], v[232:235], v[188:191], v[80:83]
	v_mfma_f32_16x16x32_bf16 v[68:71], v[208:211], v[200:203], v[68:71]
	v_mfma_f32_16x16x32_bf16 v[64:67], v[232:235], v[200:203], v[64:67]
	s_mov_b32 m0, s74
	v_lshl_add_u64 v[174:175], v[236:237], 0, s[40:41]
	s_barrier
	ds_read_b128 v[144:147], v195 offset:49152
	ds_read_b128 v[162:165], v195 offset:51200
	ds_read_b128 v[170:173], v195 offset:53248
	ds_read_b128 v[196:199], v195 offset:55296
	ds_read_b128 v[148:151], v195 offset:50176
	ds_read_b128 v[166:169], v195 offset:52224
	ds_read_b128 v[188:191], v195 offset:54272
	ds_read_b128 v[200:203], v195 offset:56320
	global_load_lds_dwordx4 v[174:175], off
	v_lshl_add_u64 v[174:175], v[238:239], 0, s[40:41]
	s_mov_b32 m0, s75
	s_nop 0
	global_load_lds_dwordx4 v[174:175], off
	s_barrier
	s_waitcnt lgkmcnt(7)
	v_mfma_f32_16x16x32_bf16 v[60:63], v[128:131], v[144:147], v[60:63]
	v_mfma_f32_16x16x32_bf16 v[56:59], v[136:139], v[144:147], v[56:59]
	s_waitcnt lgkmcnt(6)
	v_mfma_f32_16x16x32_bf16 v[44:47], v[128:131], v[162:165], v[44:47]
	v_mfma_f32_16x16x32_bf16 v[40:43], v[136:139], v[162:165], v[40:43]
	s_waitcnt lgkmcnt(5)
	v_mfma_f32_16x16x32_bf16 v[28:31], v[128:131], v[170:173], v[28:31]
	v_mfma_f32_16x16x32_bf16 v[24:27], v[136:139], v[170:173], v[24:27]
	s_waitcnt lgkmcnt(4)
	v_mfma_f32_16x16x32_bf16 v[12:15], v[128:131], v[196:199], v[12:15]
	v_mfma_f32_16x16x32_bf16 v[8:11], v[136:139], v[196:199], v[8:11]
	s_waitcnt lgkmcnt(3)
	v_mfma_f32_16x16x32_bf16 v[60:63], v[132:135], v[148:151], v[60:63]
	v_mfma_f32_16x16x32_bf16 v[56:59], v[140:143], v[148:151], v[56:59]
	s_waitcnt lgkmcnt(2)
	v_mfma_f32_16x16x32_bf16 v[44:47], v[132:135], v[166:169], v[44:47]
	v_mfma_f32_16x16x32_bf16 v[40:43], v[140:143], v[166:169], v[40:43]
	s_waitcnt lgkmcnt(1)
	v_mfma_f32_16x16x32_bf16 v[28:31], v[132:135], v[188:191], v[28:31]
	v_mfma_f32_16x16x32_bf16 v[24:27], v[140:143], v[188:191], v[24:27]
	s_waitcnt lgkmcnt(0)
	v_mfma_f32_16x16x32_bf16 v[12:15], v[132:135], v[200:203], v[12:15]
	v_mfma_f32_16x16x32_bf16 v[8:11], v[140:143], v[200:203], v[8:11]
	s_barrier
	s_add_i32 s28, s29, s47
	v_lshl_add_u64 v[128:129], v[240:241], 0, s[40:41]
	s_mov_b32 m0, s28
	s_nop 0
	global_load_lds_dwordx4 v[128:129], off
	v_lshl_add_u64 v[128:129], v[242:243], 0, s[40:41]
	s_add_i32 m0, s28, 0x2000
	s_nop 0
	global_load_lds_dwordx4 v[128:129], off
	s_waitcnt vmcnt(6)
	s_barrier
	v_mfma_f32_16x16x32_bf16 v[52:55], v[204:207], v[144:147], v[52:55]
	v_mfma_f32_16x16x32_bf16 v[48:51], v[212:215], v[144:147], v[48:51]
	v_mfma_f32_16x16x32_bf16 v[36:39], v[204:207], v[162:165], v[36:39]
	v_mfma_f32_16x16x32_bf16 v[32:35], v[212:215], v[162:165], v[32:35]
	v_mfma_f32_16x16x32_bf16 v[20:23], v[204:207], v[170:173], v[20:23]
	v_mfma_f32_16x16x32_bf16 v[16:19], v[212:215], v[170:173], v[16:19]
	v_mfma_f32_16x16x32_bf16 v[4:7], v[204:207], v[196:199], v[4:7]
	v_mfma_f32_16x16x32_bf16 v[0:3], v[212:215], v[196:199], v[0:3]
	v_mfma_f32_16x16x32_bf16 v[52:55], v[208:211], v[148:151], v[52:55]
	v_mfma_f32_16x16x32_bf16 v[48:51], v[232:235], v[148:151], v[48:51]
	v_mfma_f32_16x16x32_bf16 v[36:39], v[208:211], v[166:169], v[36:39]
	v_mfma_f32_16x16x32_bf16 v[32:35], v[232:235], v[166:169], v[32:35]
	v_mfma_f32_16x16x32_bf16 v[20:23], v[208:211], v[188:191], v[20:23]
	v_mfma_f32_16x16x32_bf16 v[16:19], v[232:235], v[188:191], v[16:19]
	v_mfma_f32_16x16x32_bf16 v[4:7], v[208:211], v[200:203], v[4:7]
	v_mfma_f32_16x16x32_bf16 v[0:3], v[232:235], v[200:203], v[0:3]
	s_add_u32 s64, s64, 0x100
	s_addc_u32 s65, s65, 0
	s_add_u32 s91, s91, 0x100
	s_addc_u32 vcc_lo, vcc_lo, 0
	s_cmp_lt_i32 vcc_hi, s76
	s_mov_b32 s66, vcc_hi
	s_barrier
	s_cbranch_scc1 .LBB0_1114
	s_lshl_b32 s28, s84, 8
	v_mov_b32_e32 v128, v193
	v_mov_b32_e32 v129, v192
	s_add_i32 s28, s28, s78
	s_lshl_b32 s64, s24, 2
	v_add_u32_e32 v166, s28, v129
	s_lshl_b32 s28, s24, 8
	s_or_b32 s28, s28, s79
	v_lshl_add_u32 v162, v128, 3, s28
	v_ashrrev_i32_e32 v163, 31, v162
	v_lshlrev_b64 v[204:205], 1, v[162:163]
	v_ashrrev_i32_e32 v167, 31, v166
	v_lshl_add_u64 v[164:165], s[12:13], 0, v[204:205]
	v_lshlrev_b64 v[206:207], 11, v[166:167]
	v_cmp_eq_u32_e32 vcc, 0, v128
	v_lshl_add_u64 v[128:129], v[164:165], 0, v[206:207]
	global_load_dwordx4 v[196:199], v[128:129], off
	global_load_dwordx4 v[200:203], v[128:129], off offset:256
	v_add_u32_e32 v188, 16, v166
	v_ashrrev_i32_e32 v189, 31, v188
	v_add_u32_e32 v172, 32, v166
	v_lshlrev_b64 v[190:191], 11, v[188:189]
	v_ashrrev_i32_e32 v173, 31, v172
	v_add_u32_e32 v168, 48, v166
	v_lshl_add_u64 v[128:129], v[164:165], 0, v[190:191]
	v_lshlrev_b64 v[174:175], 11, v[172:173]
	v_ashrrev_i32_e32 v169, 31, v168
	global_load_dwordx4 v[148:151], v[128:129], off
	global_load_dwordx4 v[144:147], v[128:129], off offset:256
	v_lshl_add_u64 v[128:129], v[164:165], 0, v[174:175]
	v_lshlrev_b64 v[170:171], 11, v[168:169]
	global_load_dwordx4 v[140:143], v[128:129], off
	global_load_dwordx4 v[136:139], v[128:129], off offset:256
	v_lshl_add_u64 v[128:129], v[164:165], 0, v[170:171]
	global_load_dwordx4 v[132:135], v[128:129], off
	s_nop 0
	global_load_dwordx4 v[128:131], v[128:129], off offset:256
	v_lshl_add_u64 v[206:207], s[12:13], 0, v[206:207]
	v_lshl_add_u64 v[204:205], v[206:207], 0, v[204:205]
	s_ashr_i32 s65, s64, 31
	s_waitcnt vmcnt(0)
	v_lshlrev_b32_e32 v208, 16, v196
	v_and_b32_e32 v209, 0xffff0000, v196
	v_lshlrev_b32_e32 v196, 16, v197
	v_and_b32_e32 v197, 0xffff0000, v197
	v_lshlrev_b32_e32 v210, 16, v198
	v_and_b32_e32 v211, 0xffff0000, v198
	v_lshlrev_b32_e32 v198, 16, v199
	v_and_b32_e32 v199, 0xffff0000, v199
	v_pk_fma_f32 v[126:127], s[62:63], v[126:127], v[196:197]
	v_pk_fma_f32 v[124:125], s[10:11], v[124:125], v[208:209]
	v_pk_fma_f32 v[196:197], s[62:63], v[122:123], v[198:199]
	v_pk_fma_f32 v[198:199], s[10:11], v[120:121], v[210:211]
	v_cvt_pk_bf16_f32 v120, v124, v125
	v_cvt_pk_bf16_f32 v121, v126, v127
	s_nop 0
	v_cvt_pk_bf16_f32 v122, v198, v199
	v_cvt_pk_bf16_f32 v123, v196, v197
	global_store_dwordx4 v[204:205], v[120:123], off
	s_nop 1
	v_pk_mul_f32 v[120:121], v[198:199], v[198:199]
	v_pk_mul_f32 v[122:123], v[196:197], v[196:197]
	v_pk_fma_f32 v[120:121], v[124:125], v[124:125], v[120:121]
	v_pk_fma_f32 v[122:123], v[126:127], v[126:127], v[122:123]
	v_add_f32_e32 v120, v120, v121
	v_add_f32_e32 v121, v122, v123
	v_add_f32_e32 v196, v120, v121
	v_lshlrev_b32_e32 v120, 16, v200
	v_and_b32_e32 v121, 0xffff0000, v200
	v_lshlrev_b32_e32 v122, 16, v201
	v_and_b32_e32 v123, 0xffff0000, v201
	v_lshlrev_b32_e32 v124, 16, v202
	v_and_b32_e32 v125, 0xffff0000, v202
	v_lshlrev_b32_e32 v126, 16, v203
	v_and_b32_e32 v127, 0xffff0000, v203
	v_pk_fma_f32 v[118:119], s[62:63], v[118:119], v[122:123]
	v_pk_fma_f32 v[116:117], s[10:11], v[116:117], v[120:121]
	v_pk_fma_f32 v[120:121], s[62:63], v[114:115], v[126:127]
	v_pk_fma_f32 v[122:123], s[10:11], v[112:113], v[124:125]
	v_cvt_pk_bf16_f32 v112, v116, v117
	v_cvt_pk_bf16_f32 v113, v118, v119
	s_nop 0
	v_cvt_pk_bf16_f32 v114, v122, v123
	v_cvt_pk_bf16_f32 v115, v120, v121
	global_store_dwordx4 v[204:205], v[112:115], off offset:256
	s_nop 1
	v_pk_mul_f32 v[112:113], v[122:123], v[122:123]
	v_pk_mul_f32 v[114:115], v[120:121], v[120:121]
	v_pk_fma_f32 v[112:113], v[116:117], v[116:117], v[112:113]
	v_pk_fma_f32 v[114:115], v[118:119], v[118:119], v[114:115]
	v_add_f32_e32 v112, v112, v113
	v_add_f32_e32 v113, v114, v115
	v_add_f32_e32 v112, v112, v113
	v_add_f32_e32 v112, v196, v112
	ds_bpermute_b32 v113, v219, v112
	s_waitcnt lgkmcnt(0)
	v_add_f32_e32 v112, v112, v113
	ds_bpermute_b32 v113, v218, v112
	s_and_saveexec_b64 s[66:67], vcc
	s_cbranch_execz .LBB0_1117
	v_lshlrev_b64 v[114:115], 6, v[166:167]
	v_lshl_add_u64 v[114:115], s[8:9], 0, v[114:115]
	v_lshl_add_u64 v[114:115], s[64:65], 2, v[114:115]
	s_lshl_b32 s24, s77, 2
	v_lshl_add_u64 v[114:115], v[114:115], 0, s[24:25]
	s_waitcnt lgkmcnt(0)
	v_add_f32_e32 v112, v112, v113
	global_store_dword v[114:115], v112, off

.LBB0_1282:
	s_add_i32 s81, s60, 2
	s_add_u32 s28, s58, 0x80
	s_addc_u32 s29, s59, 0
	s_add_i32 s82, 0, 0x10000
	v_add_u32_e32 v140, s82, v195
	ds_read_b128 v[128:131], v140
	ds_read_b128 v[132:135], v140 offset:1024
	ds_read_b128 v[136:139], v140 offset:2048
	ds_read_b128 v[140:143], v140 offset:3072
	s_cmp_eq_u32 s5, s60
	s_cselect_b32 s60, s56, s28
	s_cselect_b32 s61, s57, s29
	s_cselect_b32 s63, s3, s80
	s_cselect_b32 s62, s2, s21
	s_add_i32 m0, s66, 0xc000
	ds_read_b128 v[144:147], v196
	ds_read_b128 v[162:165], v196 offset:2048
	ds_read_b128 v[170:173], v196 offset:4096
	ds_read_b128 v[198:201], v196 offset:6144
	ds_read_b128 v[148:151], v196 offset:1024
	ds_read_b128 v[166:169], v196 offset:3072
	ds_read_b128 v[188:191], v196 offset:5120
	ds_read_b128 v[202:205], v196 offset:7168
	global_load_lds_dwordx4 v158, s[58:59]
	v_lshl_add_u64 v[174:175], s[58:59], 0, v[160:161]
	s_add_i32 m0, s66, 0xe000
	s_nop 0
	global_load_lds_dwordx4 v[174:175], off
	s_waitcnt lgkmcnt(8)
	s_barrier
	s_waitcnt lgkmcnt(7)
	v_mfma_f32_16x16x32_bf16 v[124:127], v[128:131], v[144:147], v[124:127]
	v_mfma_f32_16x16x32_bf16 v[120:123], v[136:139], v[144:147], v[120:123]
	s_waitcnt lgkmcnt(6)
	v_mfma_f32_16x16x32_bf16 v[108:111], v[128:131], v[162:165], v[108:111]
	v_mfma_f32_16x16x32_bf16 v[104:107], v[136:139], v[162:165], v[104:107]
	s_waitcnt lgkmcnt(5)
	v_mfma_f32_16x16x32_bf16 v[92:95], v[128:131], v[170:173], v[92:95]
	v_mfma_f32_16x16x32_bf16 v[88:91], v[136:139], v[170:173], v[88:91]
	s_waitcnt lgkmcnt(4)
	v_mfma_f32_16x16x32_bf16 v[76:79], v[128:131], v[198:201], v[76:79]
	v_mfma_f32_16x16x32_bf16 v[72:75], v[136:139], v[198:201], v[72:75]
	s_waitcnt lgkmcnt(3)
	v_mfma_f32_16x16x32_bf16 v[124:127], v[132:135], v[148:151], v[124:127]
	v_mfma_f32_16x16x32_bf16 v[120:123], v[140:143], v[148:151], v[120:123]
	s_waitcnt lgkmcnt(2)
	v_mfma_f32_16x16x32_bf16 v[108:111], v[132:135], v[166:169], v[108:111]
	v_mfma_f32_16x16x32_bf16 v[104:107], v[140:143], v[166:169], v[104:107]
	s_waitcnt lgkmcnt(1)
	v_mfma_f32_16x16x32_bf16 v[92:95], v[132:135], v[188:191], v[92:95]
	v_mfma_f32_16x16x32_bf16 v[88:91], v[140:143], v[188:191], v[88:91]
	s_waitcnt lgkmcnt(0)
	v_mfma_f32_16x16x32_bf16 v[76:79], v[132:135], v[202:205], v[76:79]
	v_mfma_f32_16x16x32_bf16 v[72:75], v[140:143], v[202:205], v[72:75]
	s_barrier
	s_add_i32 s28, 0, 0x14000
	v_add_u32_e32 v174, s28, v195
	s_add_i32 s29, s82, s65
	ds_read_b128 v[206:209], v174
	ds_read_b128 v[210:213], v174 offset:1024
	ds_read_b128 v[214:217], v174 offset:2048
	ds_read_b128 v[232:235], v174 offset:3072
	v_lshl_add_u64 v[174:175], s[62:63], 0, v[176:177]
	s_mov_b32 m0, s29
	v_lshl_add_u64 v[236:237], s[62:63], 0, v[156:157]
	global_load_lds_dwordx4 v[174:175], off
	s_add_i32 m0, s29, 0x2000
	s_nop 0
	global_load_lds_dwordx4 v[236:237], off
	s_barrier
	s_waitcnt lgkmcnt(3)
	v_mfma_f32_16x16x32_bf16 v[116:119], v[206:209], v[144:147], v[116:119]
	s_waitcnt lgkmcnt(1)
	v_mfma_f32_16x16x32_bf16 v[112:115], v[214:217], v[144:147], v[112:115]
	v_mfma_f32_16x16x32_bf16 v[100:103], v[206:209], v[162:165], v[100:103]
	v_mfma_f32_16x16x32_bf16 v[96:99], v[214:217], v[162:165], v[96:99]
	v_mfma_f32_16x16x32_bf16 v[84:87], v[206:209], v[170:173], v[84:87]
	v_mfma_f32_16x16x32_bf16 v[80:83], v[214:217], v[170:173], v[80:83]
	v_mfma_f32_16x16x32_bf16 v[68:71], v[206:209], v[198:201], v[68:71]
	v_mfma_f32_16x16x32_bf16 v[64:67], v[214:217], v[198:201], v[64:67]
	v_mfma_f32_16x16x32_bf16 v[116:119], v[210:213], v[148:151], v[116:119]
	s_waitcnt lgkmcnt(0)
	v_mfma_f32_16x16x32_bf16 v[112:115], v[232:235], v[148:151], v[112:115]
	v_mfma_f32_16x16x32_bf16 v[100:103], v[210:213], v[166:169], v[100:103]
	v_mfma_f32_16x16x32_bf16 v[96:99], v[232:235], v[166:169], v[96:99]
	v_mfma_f32_16x16x32_bf16 v[84:87], v[210:213], v[188:191], v[84:87]
	v_mfma_f32_16x16x32_bf16 v[80:83], v[232:235], v[188:191], v[80:83]
	v_mfma_f32_16x16x32_bf16 v[68:71], v[210:213], v[202:205], v[68:71]
	v_mfma_f32_16x16x32_bf16 v[64:67], v[232:235], v[202:205], v[64:67]
	s_mov_b32 m0, s66
	v_lshl_add_u64 v[238:239], s[60:61], 0, v[152:153]
	s_barrier
	ds_read_b128 v[144:147], v196 offset:16384
	ds_read_b128 v[162:165], v196 offset:18432
	ds_read_b128 v[170:173], v196 offset:20480
	ds_read_b128 v[198:201], v196 offset:22528
	ds_read_b128 v[148:151], v196 offset:17408
	ds_read_b128 v[166:169], v196 offset:19456
	ds_read_b128 v[188:191], v196 offset:21504
	ds_read_b128 v[202:205], v196 offset:23552
	global_load_lds_dwordx4 v[238:239], off
	v_lshl_add_u64 v[240:241], s[60:61], 0, v[154:155]
	s_mov_b32 m0, s67
	s_nop 0
	global_load_lds_dwordx4 v[240:241], off
	s_barrier
	s_waitcnt lgkmcnt(7)
	v_mfma_f32_16x16x32_bf16 v[60:63], v[128:131], v[144:147], v[60:63]
	v_mfma_f32_16x16x32_bf16 v[56:59], v[136:139], v[144:147], v[56:59]
	s_waitcnt lgkmcnt(6)
	v_mfma_f32_16x16x32_bf16 v[44:47], v[128:131], v[162:165], v[44:47]
	v_mfma_f32_16x16x32_bf16 v[40:43], v[136:139], v[162:165], v[40:43]
	s_waitcnt lgkmcnt(5)
	v_mfma_f32_16x16x32_bf16 v[28:31], v[128:131], v[170:173], v[28:31]
	v_mfma_f32_16x16x32_bf16 v[24:27], v[136:139], v[170:173], v[24:27]
	s_waitcnt lgkmcnt(4)
	v_mfma_f32_16x16x32_bf16 v[12:15], v[128:131], v[198:201], v[12:15]
	v_mfma_f32_16x16x32_bf16 v[8:11], v[136:139], v[198:201], v[8:11]
	s_waitcnt lgkmcnt(3)
	v_mfma_f32_16x16x32_bf16 v[60:63], v[132:135], v[148:151], v[60:63]
	v_mfma_f32_16x16x32_bf16 v[56:59], v[140:143], v[148:151], v[56:59]
	s_waitcnt lgkmcnt(2)
	v_mfma_f32_16x16x32_bf16 v[44:47], v[132:135], v[166:169], v[44:47]
	v_mfma_f32_16x16x32_bf16 v[40:43], v[140:143], v[166:169], v[40:43]
	s_waitcnt lgkmcnt(1)
	v_mfma_f32_16x16x32_bf16 v[28:31], v[132:135], v[188:191], v[28:31]
	v_mfma_f32_16x16x32_bf16 v[24:27], v[140:143], v[188:191], v[24:27]
	s_waitcnt lgkmcnt(0)
	v_mfma_f32_16x16x32_bf16 v[12:15], v[132:135], v[202:205], v[12:15]
	v_mfma_f32_16x16x32_bf16 v[8:11], v[140:143], v[202:205], v[8:11]
	s_barrier
	s_add_u32 s62, s62, s4
	s_addc_u32 s63, s63, 0
	s_add_i32 s28, s28, s65
	v_lshl_add_u64 v[242:243], s[62:63], 0, v[176:177]
	s_mov_b32 m0, s28
	v_lshl_add_u64 v[244:245], s[62:63], 0, v[156:157]
	global_load_lds_dwordx4 v[242:243], off
	s_add_i32 m0, s28, 0x2000
	s_nop 0
	global_load_lds_dwordx4 v[244:245], off
	s_waitcnt vmcnt(6)
	s_barrier
	v_mfma_f32_16x16x32_bf16 v[52:55], v[206:209], v[144:147], v[52:55]
	v_mfma_f32_16x16x32_bf16 v[48:51], v[214:217], v[144:147], v[48:51]
	v_mfma_f32_16x16x32_bf16 v[36:39], v[206:209], v[162:165], v[36:39]
	v_mfma_f32_16x16x32_bf16 v[32:35], v[214:217], v[162:165], v[32:35]
	v_mfma_f32_16x16x32_bf16 v[20:23], v[206:209], v[170:173], v[20:23]
	v_mfma_f32_16x16x32_bf16 v[16:19], v[214:217], v[170:173], v[16:19]
	v_mfma_f32_16x16x32_bf16 v[4:7], v[206:209], v[198:201], v[4:7]
	v_mfma_f32_16x16x32_bf16 v[0:3], v[214:217], v[198:201], v[0:3]
	v_mfma_f32_16x16x32_bf16 v[52:55], v[210:213], v[148:151], v[52:55]
	v_mfma_f32_16x16x32_bf16 v[48:51], v[232:235], v[148:151], v[48:51]
	v_mfma_f32_16x16x32_bf16 v[36:39], v[210:213], v[166:169], v[36:39]
	v_mfma_f32_16x16x32_bf16 v[32:35], v[232:235], v[166:169], v[32:35]
	v_mfma_f32_16x16x32_bf16 v[20:23], v[210:213], v[188:191], v[20:23]
	v_mfma_f32_16x16x32_bf16 v[16:19], v[232:235], v[188:191], v[16:19]
	v_mfma_f32_16x16x32_bf16 v[4:7], v[210:213], v[202:205], v[4:7]
	v_mfma_f32_16x16x32_bf16 v[0:3], v[232:235], v[202:205], v[0:3]
	s_add_i32 s28, 0, 0x18000
	v_add_u32_e32 v140, s28, v195
	s_barrier
	ds_read_b128 v[128:131], v140
	ds_read_b128 v[132:135], v140 offset:1024
	ds_read_b128 v[136:139], v140 offset:2048
	ds_read_b128 v[140:143], v140 offset:3072
	s_add_u32 s60, s60, s4
	s_addc_u32 s61, s61, 0
	s_mov_b32 m0, s68
	ds_read_b128 v[144:147], v196 offset:32768
	ds_read_b128 v[162:165], v196 offset:34816
	ds_read_b128 v[170:173], v196 offset:36864
	ds_read_b128 v[198:201], v196 offset:38912
	ds_read_b128 v[148:151], v196 offset:33792
	ds_read_b128 v[166:169], v196 offset:35840
	ds_read_b128 v[188:191], v196 offset:37888
	ds_read_b128 v[202:205], v196 offset:39936
	global_load_lds_dwordx4 v152, s[60:61]
	s_mov_b32 m0, s69
	s_nop 0
	global_load_lds_dwordx4 v154, s[60:61]
	s_waitcnt lgkmcnt(8)
	s_barrier
	s_waitcnt lgkmcnt(7)
	v_mfma_f32_16x16x32_bf16 v[124:127], v[128:131], v[144:147], v[124:127]
	v_mfma_f32_16x16x32_bf16 v[120:123], v[136:139], v[144:147], v[120:123]
	s_waitcnt lgkmcnt(6)
	v_mfma_f32_16x16x32_bf16 v[108:111], v[128:131], v[162:165], v[108:111]
	v_mfma_f32_16x16x32_bf16 v[104:107], v[136:139], v[162:165], v[104:107]
	s_waitcnt lgkmcnt(5)
	v_mfma_f32_16x16x32_bf16 v[92:95], v[128:131], v[170:173], v[92:95]
	v_mfma_f32_16x16x32_bf16 v[88:91], v[136:139], v[170:173], v[88:91]
	s_waitcnt lgkmcnt(4)
	v_mfma_f32_16x16x32_bf16 v[76:79], v[128:131], v[198:201], v[76:79]
	v_mfma_f32_16x16x32_bf16 v[72:75], v[136:139], v[198:201], v[72:75]
	s_waitcnt lgkmcnt(3)
	v_mfma_f32_16x16x32_bf16 v[124:127], v[132:135], v[148:151], v[124:127]
	v_mfma_f32_16x16x32_bf16 v[120:123], v[140:143], v[148:151], v[120:123]
	s_waitcnt lgkmcnt(2)
	v_mfma_f32_16x16x32_bf16 v[108:111], v[132:135], v[166:169], v[108:111]
	v_mfma_f32_16x16x32_bf16 v[104:107], v[140:143], v[166:169], v[104:107]
	s_waitcnt lgkmcnt(1)
	v_mfma_f32_16x16x32_bf16 v[92:95], v[132:135], v[188:191], v[92:95]
	v_mfma_f32_16x16x32_bf16 v[88:91], v[140:143], v[188:191], v[88:91]
	s_waitcnt lgkmcnt(0)
	v_mfma_f32_16x16x32_bf16 v[76:79], v[132:135], v[202:205], v[76:79]
	v_mfma_f32_16x16x32_bf16 v[72:75], v[140:143], v[202:205], v[72:75]
	s_barrier
	s_add_i32 s29, 0, 0x1c000
	s_add_i32 s28, s28, s65
	v_add_u32_e32 v197, s29, v195
	v_lshl_add_u64 v[174:175], v[174:175], 0, s[40:41]
	s_mov_b32 m0, s28
	ds_read_b128 v[206:209], v197
	ds_read_b128 v[210:213], v197 offset:1024
	ds_read_b128 v[214:217], v197 offset:2048
	ds_read_b128 v[232:235], v197 offset:3072
	global_load_lds_dwordx4 v[174:175], off
	v_lshl_add_u64 v[174:175], v[236:237], 0, s[40:41]
	s_add_i32 m0, s28, 0x2000
	s_nop 0
	global_load_lds_dwordx4 v[174:175], off
	s_barrier
	s_waitcnt lgkmcnt(3)
	v_mfma_f32_16x16x32_bf16 v[116:119], v[206:209], v[144:147], v[116:119]
	s_waitcnt lgkmcnt(1)
	v_mfma_f32_16x16x32_bf16 v[112:115], v[214:217], v[144:147], v[112:115]
	v_mfma_f32_16x16x32_bf16 v[100:103], v[206:209], v[162:165], v[100:103]
	v_mfma_f32_16x16x32_bf16 v[96:99], v[214:217], v[162:165], v[96:99]
	v_mfma_f32_16x16x32_bf16 v[84:87], v[206:209], v[170:173], v[84:87]
	v_mfma_f32_16x16x32_bf16 v[80:83], v[214:217], v[170:173], v[80:83]
	v_mfma_f32_16x16x32_bf16 v[68:71], v[206:209], v[198:201], v[68:71]
	v_mfma_f32_16x16x32_bf16 v[64:67], v[214:217], v[198:201], v[64:67]
	v_mfma_f32_16x16x32_bf16 v[116:119], v[210:213], v[148:151], v[116:119]
	s_waitcnt lgkmcnt(0)
	v_mfma_f32_16x16x32_bf16 v[112:115], v[232:235], v[148:151], v[112:115]
	v_mfma_f32_16x16x32_bf16 v[100:103], v[210:213], v[166:169], v[100:103]
	v_mfma_f32_16x16x32_bf16 v[96:99], v[232:235], v[166:169], v[96:99]
	v_mfma_f32_16x16x32_bf16 v[84:87], v[210:213], v[188:191], v[84:87]
	v_mfma_f32_16x16x32_bf16 v[80:83], v[232:235], v[188:191], v[80:83]
	v_mfma_f32_16x16x32_bf16 v[68:71], v[210:213], v[202:205], v[68:71]
	v_mfma_f32_16x16x32_bf16 v[64:67], v[232:235], v[202:205], v[64:67]
	s_mov_b32 m0, s71
	v_lshl_add_u64 v[174:175], v[238:239], 0, s[40:41]
	s_barrier
	ds_read_b128 v[144:147], v196 offset:49152
	ds_read_b128 v[162:165], v196 offset:51200
	ds_read_b128 v[170:173], v196 offset:53248
	ds_read_b128 v[198:201], v196 offset:55296
	ds_read_b128 v[148:151], v196 offset:50176
	ds_read_b128 v[166:169], v196 offset:52224
	ds_read_b128 v[188:191], v196 offset:54272
	ds_read_b128 v[202:205], v196 offset:56320
	global_load_lds_dwordx4 v[174:175], off
	v_lshl_add_u64 v[174:175], v[240:241], 0, s[40:41]
	s_mov_b32 m0, s72
	s_nop 0
	global_load_lds_dwordx4 v[174:175], off
	s_barrier
	s_waitcnt lgkmcnt(7)
	v_mfma_f32_16x16x32_bf16 v[60:63], v[128:131], v[144:147], v[60:63]
	v_mfma_f32_16x16x32_bf16 v[56:59], v[136:139], v[144:147], v[56:59]
	s_waitcnt lgkmcnt(6)
	v_mfma_f32_16x16x32_bf16 v[44:47], v[128:131], v[162:165], v[44:47]
	v_mfma_f32_16x16x32_bf16 v[40:43], v[136:139], v[162:165], v[40:43]
	s_waitcnt lgkmcnt(5)
	v_mfma_f32_16x16x32_bf16 v[28:31], v[128:131], v[170:173], v[28:31]
	v_mfma_f32_16x16x32_bf16 v[24:27], v[136:139], v[170:173], v[24:27]
	s_waitcnt lgkmcnt(4)
	v_mfma_f32_16x16x32_bf16 v[12:15], v[128:131], v[198:201], v[12:15]
	v_mfma_f32_16x16x32_bf16 v[8:11], v[136:139], v[198:201], v[8:11]
	s_waitcnt lgkmcnt(3)
	v_mfma_f32_16x16x32_bf16 v[60:63], v[132:135], v[148:151], v[60:63]
	v_mfma_f32_16x16x32_bf16 v[56:59], v[140:143], v[148:151], v[56:59]
	s_waitcnt lgkmcnt(2)
	v_mfma_f32_16x16x32_bf16 v[44:47], v[132:135], v[166:169], v[44:47]
	v_mfma_f32_16x16x32_bf16 v[40:43], v[140:143], v[166:169], v[40:43]
	s_waitcnt lgkmcnt(1)
	v_mfma_f32_16x16x32_bf16 v[28:31], v[132:135], v[188:191], v[28:31]
	v_mfma_f32_16x16x32_bf16 v[24:27], v[140:143], v[188:191], v[24:27]
	s_waitcnt lgkmcnt(0)
	v_mfma_f32_16x16x32_bf16 v[12:15], v[132:135], v[202:205], v[12:15]
	v_mfma_f32_16x16x32_bf16 v[8:11], v[140:143], v[202:205], v[8:11]
	s_barrier
	s_add_i32 s28, s29, s65
	v_lshl_add_u64 v[128:129], v[242:243], 0, s[40:41]
	s_mov_b32 m0, s28
	s_nop 0
	global_load_lds_dwordx4 v[128:129], off
	v_lshl_add_u64 v[128:129], v[244:245], 0, s[40:41]
	s_add_i32 m0, s28, 0x2000
	s_nop 0
	global_load_lds_dwordx4 v[128:129], off
	s_waitcnt vmcnt(6)
	s_barrier
	v_mfma_f32_16x16x32_bf16 v[52:55], v[206:209], v[144:147], v[52:55]
	v_mfma_f32_16x16x32_bf16 v[48:51], v[214:217], v[144:147], v[48:51]
	v_mfma_f32_16x16x32_bf16 v[36:39], v[206:209], v[162:165], v[36:39]
	v_mfma_f32_16x16x32_bf16 v[32:35], v[214:217], v[162:165], v[32:35]
	v_mfma_f32_16x16x32_bf16 v[20:23], v[206:209], v[170:173], v[20:23]
	v_mfma_f32_16x16x32_bf16 v[16:19], v[214:217], v[170:173], v[16:19]
	v_mfma_f32_16x16x32_bf16 v[4:7], v[206:209], v[198:201], v[4:7]
	v_mfma_f32_16x16x32_bf16 v[0:3], v[214:217], v[198:201], v[0:3]
	v_mfma_f32_16x16x32_bf16 v[52:55], v[210:213], v[148:151], v[52:55]
	v_mfma_f32_16x16x32_bf16 v[48:51], v[232:235], v[148:151], v[48:51]
	v_mfma_f32_16x16x32_bf16 v[36:39], v[210:213], v[166:169], v[36:39]
	v_mfma_f32_16x16x32_bf16 v[32:35], v[232:235], v[166:169], v[32:35]
	v_mfma_f32_16x16x32_bf16 v[20:23], v[210:213], v[188:191], v[20:23]
	v_mfma_f32_16x16x32_bf16 v[16:19], v[232:235], v[188:191], v[16:19]
	v_mfma_f32_16x16x32_bf16 v[4:7], v[210:213], v[202:205], v[4:7]
	v_mfma_f32_16x16x32_bf16 v[0:3], v[232:235], v[202:205], v[0:3]
	s_add_u32 s58, s58, 0x100
	s_addc_u32 s59, s59, 0
	s_add_u32 s21, s21, 0x100
	s_addc_u32 s80, s80, 0
	s_cmp_ge_i32 s81, s79
	s_mov_b32 s60, s81
	s_barrier
	s_cbranch_scc0 .LBB0_1282
	s_cmp_gt_i32 s24, -1
	s_mov_b64 s[58:59], -1
	s_cbranch_scc0 .LBB0_1285
	s_lshl_b64 s[58:59], s[24:25], 17
	v_mov_b32_e32 v128, v231
	s_add_u32 s58, s37, s58
	s_addc_u32 s59, s46, s59
	v_ashrrev_i32_e32 v129, 31, v128
	v_lshl_add_u64 v[128:129], v[128:129], 4, s[58:59]
	v_add_co_u32_e32 v134, vcc, s36, v128
	v_cvt_pk_bf16_f32 v130, v124, v125
	v_cvt_pk_bf16_f32 v131, v126, v127
	v_cvt_pk_bf16_f32 v132, v120, v121
	v_cvt_pk_bf16_f32 v133, v122, v123
	s_nop 1
	v_addc_co_u32_e32 v135, vcc, 0, v129, vcc
	s_movk_i32 s5, 0x4000
	global_store_dwordx4 v[128:129], v[130:133], off
	s_mov_b64 s[58:59], 0
	s_nop 0
	v_cvt_pk_bf16_f32 v130, v108, v109
	v_cvt_pk_bf16_f32 v131, v110, v111
	v_cvt_pk_bf16_f32 v132, v104, v105
	v_cvt_pk_bf16_f32 v133, v106, v107
	global_store_dwordx4 v[134:135], v[130:133], off
	v_add_co_u32_e32 v134, vcc, s5, v128
	s_movk_i32 s5, 0x6000
	s_nop 0
	v_addc_co_u32_e32 v135, vcc, 0, v129, vcc
	v_cvt_pk_bf16_f32 v130, v92, v93
	v_cvt_pk_bf16_f32 v131, v94, v95
	v_cvt_pk_bf16_f32 v132, v88, v89
	v_cvt_pk_bf16_f32 v133, v90, v91
	global_store_dwordx4 v[134:135], v[130:133], off
	v_add_co_u32_e32 v134, vcc, s5, v128
	s_nop 0
	v_cvt_pk_bf16_f32 v130, v76, v77
	v_cvt_pk_bf16_f32 v131, v78, v79
	v_cvt_pk_bf16_f32 v132, v72, v73
	v_cvt_pk_bf16_f32 v133, v74, v75
	s_nop 0
	v_addc_co_u32_e32 v135, vcc, 0, v129, vcc
	global_store_dwordx4 v[134:135], v[130:133], off
	v_add_co_u32_e32 v134, vcc, s92, v128
	s_mov_b32 s5, 0xa000
	s_nop 0
	v_addc_co_u32_e32 v135, vcc, 0, v129, vcc
	v_cvt_pk_bf16_f32 v130, v116, v117
	v_cvt_pk_bf16_f32 v131, v118, v119
	v_cvt_pk_bf16_f32 v132, v112, v113
	v_cvt_pk_bf16_f32 v133, v114, v115
	global_store_dwordx4 v[134:135], v[130:133], off
	v_add_co_u32_e32 v134, vcc, s5, v128
	s_mov_b32 s5, 0xc000
	s_nop 0
	v_addc_co_u32_e32 v135, vcc, 0, v129, vcc
	v_cvt_pk_bf16_f32 v130, v100, v101
	v_cvt_pk_bf16_f32 v131, v102, v103
	v_cvt_pk_bf16_f32 v132, v96, v97
	v_cvt_pk_bf16_f32 v133, v98, v99
	global_store_dwordx4 v[134:135], v[130:133], off
	v_add_co_u32_e32 v134, vcc, s5, v128
	s_mov_b32 s5, 0xe000
	s_nop 0
	v_addc_co_u32_e32 v135, vcc, 0, v129, vcc
	v_cvt_pk_bf16_f32 v130, v84, v85
	v_cvt_pk_bf16_f32 v131, v86, v87
	v_cvt_pk_bf16_f32 v132, v80, v81
	v_cvt_pk_bf16_f32 v133, v82, v83
	global_store_dwordx4 v[134:135], v[130:133], off
	v_add_co_u32_e32 v134, vcc, s5, v128
	s_mov_b32 s5, 0x10000
	s_nop 0
	v_addc_co_u32_e32 v135, vcc, 0, v129, vcc
	v_cvt_pk_bf16_f32 v130, v68, v69
	v_cvt_pk_bf16_f32 v131, v70, v71
	v_cvt_pk_bf16_f32 v132, v64, v65
	v_cvt_pk_bf16_f32 v133, v66, v67
	global_store_dwordx4 v[134:135], v[130:133], off
	v_add_co_u32_e32 v134, vcc, s5, v128
	s_mov_b32 s5, 0x12000
	s_nop 0
	v_addc_co_u32_e32 v135, vcc, 0, v129, vcc
	v_cvt_pk_bf16_f32 v130, v60, v61
	v_cvt_pk_bf16_f32 v131, v62, v63
	v_cvt_pk_bf16_f32 v132, v56, v57
	v_cvt_pk_bf16_f32 v133, v58, v59
	global_store_dwordx4 v[134:135], v[130:133], off
	v_add_co_u32_e32 v134, vcc, s5, v128
	s_mov_b32 s5, 0x14000
	s_nop 0
	v_addc_co_u32_e32 v135, vcc, 0, v129, vcc
	v_cvt_pk_bf16_f32 v130, v44, v45
	v_cvt_pk_bf16_f32 v131, v46, v47
	v_cvt_pk_bf16_f32 v132, v40, v41
	v_cvt_pk_bf16_f32 v133, v42, v43
	global_store_dwordx4 v[134:135], v[130:133], off
	v_add_co_u32_e32 v134, vcc, s5, v128
	s_mov_b32 s5, 0x16000
	s_nop 0
	v_addc_co_u32_e32 v135, vcc, 0, v129, vcc
	v_cvt_pk_bf16_f32 v130, v28, v29
	v_cvt_pk_bf16_f32 v131, v30, v31
	v_cvt_pk_bf16_f32 v132, v24, v25
	v_cvt_pk_bf16_f32 v133, v26, v27
	global_store_dwordx4 v[134:135], v[130:133], off
	v_add_co_u32_e32 v134, vcc, s5, v128
	s_mov_b32 s5, 0x18000
	s_nop 0
	v_addc_co_u32_e32 v135, vcc, 0, v129, vcc
	v_cvt_pk_bf16_f32 v130, v12, v13
	v_cvt_pk_bf16_f32 v131, v14, v15
	v_cvt_pk_bf16_f32 v132, v8, v9
	v_cvt_pk_bf16_f32 v133, v10, v11
	global_store_dwordx4 v[134:135], v[130:133], off
	v_add_co_u32_e32 v134, vcc, s5, v128
	s_mov_b32 s5, 0x1a000
	s_nop 0
	v_addc_co_u32_e32 v135, vcc, 0, v129, vcc
	v_cvt_pk_bf16_f32 v130, v52, v53
	v_cvt_pk_bf16_f32 v131, v54, v55
	v_cvt_pk_bf16_f32 v132, v48, v49
	v_cvt_pk_bf16_f32 v133, v50, v51
	global_store_dwordx4 v[134:135], v[130:133], off
	v_add_co_u32_e32 v134, vcc, s5, v128
	s_mov_b32 s5, 0x1c000
	s_nop 0
	v_addc_co_u32_e32 v135, vcc, 0, v129, vcc
	v_cvt_pk_bf16_f32 v130, v36, v37
	v_cvt_pk_bf16_f32 v131, v38, v39
	v_cvt_pk_bf16_f32 v132, v32, v33
	v_cvt_pk_bf16_f32 v133, v34, v35
	global_store_dwordx4 v[134:135], v[130:133], off
	v_add_co_u32_e32 v134, vcc, s5, v128
	s_nop 0
	v_cvt_pk_bf16_f32 v130, v20, v21
	v_cvt_pk_bf16_f32 v131, v22, v23
	v_cvt_pk_bf16_f32 v132, v16, v17
	v_cvt_pk_bf16_f32 v133, v18, v19
	s_nop 0
	v_addc_co_u32_e32 v135, vcc, 0, v129, vcc
	v_add_co_u32_e32 v128, vcc, 0x1e000, v128
	global_store_dwordx4 v[134:135], v[130:133], off
	s_nop 0
	v_addc_co_u32_e32 v129, vcc, 0, v129, vcc
	v_cvt_pk_bf16_f32 v130, v4, v5
	v_cvt_pk_bf16_f32 v131, v6, v7
	v_cvt_pk_bf16_f32 v132, v0, v1
	v_cvt_pk_bf16_f32 v133, v2, v3
	global_store_dwordx4 v[128:129], v[130:133], off

.LBB0_1436:
	s_add_u32 s28, s6, 0xfffc0080
	s_addc_u32 s29, s7, -1
	s_add_i32 s71, 0, 0x10000
	v_add_u32_e32 v140, s71, v200
	ds_read_b128 v[128:131], v140
	ds_read_b128 v[132:135], v140 offset:1024
	ds_read_b128 v[136:139], v140 offset:2048
	ds_read_b128 v[140:143], v140 offset:3072
	s_cmp_eq_u32 s70, 12
	s_cselect_b32 s53, s17, s29
	s_cselect_b32 s52, s66, s28
	s_cselect_b32 s51, s13, s69
	s_cselect_b32 s50, s67, s68
	s_add_i32 m0, s56, 0xc000
	ds_read_b128 v[144:147], v201
	ds_read_b128 v[152:155], v201 offset:2048
	ds_read_b128 v[170:173], v201 offset:4096
	ds_read_b128 v[192:195], v201 offset:6144
	ds_read_b128 v[148:151], v201 offset:1024
	ds_read_b128 v[166:169], v201 offset:3072
	ds_read_b128 v[188:191], v201 offset:5120
	ds_read_b128 v[202:205], v201 offset:7168
	global_load_lds_dwordx4 v162, s[6:7]
	v_lshl_add_u64 v[174:175], s[6:7], 0, v[164:165]
	s_add_i32 m0, s56, 0xe000
	s_nop 0
	global_load_lds_dwordx4 v[174:175], off
	s_waitcnt lgkmcnt(8)
	s_barrier
	s_waitcnt lgkmcnt(7)
	v_mfma_f32_16x16x32_bf16 v[124:127], v[128:131], v[144:147], v[124:127]
	v_mfma_f32_16x16x32_bf16 v[116:119], v[136:139], v[144:147], v[116:119]
	s_waitcnt lgkmcnt(6)
	v_mfma_f32_16x16x32_bf16 v[108:111], v[128:131], v[152:155], v[108:111]
	v_mfma_f32_16x16x32_bf16 v[100:103], v[136:139], v[152:155], v[100:103]
	s_waitcnt lgkmcnt(5)
	v_mfma_f32_16x16x32_bf16 v[92:95], v[128:131], v[170:173], v[92:95]
	v_mfma_f32_16x16x32_bf16 v[84:87], v[136:139], v[170:173], v[84:87]
	s_waitcnt lgkmcnt(4)
	v_mfma_f32_16x16x32_bf16 v[76:79], v[128:131], v[192:195], v[76:79]
	v_mfma_f32_16x16x32_bf16 v[68:71], v[136:139], v[192:195], v[68:71]
	s_waitcnt lgkmcnt(3)
	v_mfma_f32_16x16x32_bf16 v[124:127], v[132:135], v[148:151], v[124:127]
	v_mfma_f32_16x16x32_bf16 v[116:119], v[140:143], v[148:151], v[116:119]
	s_waitcnt lgkmcnt(2)
	v_mfma_f32_16x16x32_bf16 v[108:111], v[132:135], v[166:169], v[108:111]
	v_mfma_f32_16x16x32_bf16 v[100:103], v[140:143], v[166:169], v[100:103]
	s_waitcnt lgkmcnt(1)
	v_mfma_f32_16x16x32_bf16 v[92:95], v[132:135], v[188:191], v[92:95]
	v_mfma_f32_16x16x32_bf16 v[84:87], v[140:143], v[188:191], v[84:87]
	s_waitcnt lgkmcnt(0)
	v_mfma_f32_16x16x32_bf16 v[76:79], v[132:135], v[202:205], v[76:79]
	v_mfma_f32_16x16x32_bf16 v[68:71], v[140:143], v[202:205], v[68:71]
	s_barrier
	s_add_i32 s28, 0, 0x14000
	v_add_u32_e32 v174, s28, v200
	s_add_i32 s29, s71, s55
	ds_read_b128 v[206:209], v174
	ds_read_b128 v[210:213], v174 offset:1024
	ds_read_b128 v[214:217], v174 offset:2048
	ds_read_b128 v[232:235], v174 offset:3072
	v_lshl_add_u64 v[174:175], s[50:51], 0, v[176:177]
	s_mov_b32 m0, s29
	v_lshl_add_u64 v[196:197], s[50:51], 0, v[160:161]
	global_load_lds_dwordx4 v[174:175], off
	s_add_i32 m0, s29, 0x2000
	s_nop 0
	global_load_lds_dwordx4 v[196:197], off
	s_barrier
	s_waitcnt lgkmcnt(3)
	v_mfma_f32_16x16x32_bf16 v[120:123], v[206:209], v[144:147], v[120:123]
	s_waitcnt lgkmcnt(1)
	v_mfma_f32_16x16x32_bf16 v[112:115], v[214:217], v[144:147], v[112:115]
	v_mfma_f32_16x16x32_bf16 v[104:107], v[206:209], v[152:155], v[104:107]
	v_mfma_f32_16x16x32_bf16 v[96:99], v[214:217], v[152:155], v[96:99]
	v_mfma_f32_16x16x32_bf16 v[88:91], v[206:209], v[170:173], v[88:91]
	v_mfma_f32_16x16x32_bf16 v[80:83], v[214:217], v[170:173], v[80:83]
	v_mfma_f32_16x16x32_bf16 v[72:75], v[206:209], v[192:195], v[72:75]
	v_mfma_f32_16x16x32_bf16 v[64:67], v[214:217], v[192:195], v[64:67]
	v_mfma_f32_16x16x32_bf16 v[120:123], v[210:213], v[148:151], v[120:123]
	s_waitcnt lgkmcnt(0)
	v_mfma_f32_16x16x32_bf16 v[112:115], v[232:235], v[148:151], v[112:115]
	v_mfma_f32_16x16x32_bf16 v[104:107], v[210:213], v[166:169], v[104:107]
	v_mfma_f32_16x16x32_bf16 v[96:99], v[232:235], v[166:169], v[96:99]
	v_mfma_f32_16x16x32_bf16 v[88:91], v[210:213], v[188:191], v[88:91]
	v_mfma_f32_16x16x32_bf16 v[80:83], v[232:235], v[188:191], v[80:83]
	v_mfma_f32_16x16x32_bf16 v[72:75], v[210:213], v[202:205], v[72:75]
	v_mfma_f32_16x16x32_bf16 v[64:67], v[232:235], v[202:205], v[64:67]
	s_mov_b32 m0, s56
	v_lshl_add_u64 v[236:237], s[52:53], 0, v[156:157]
	s_barrier
	ds_read_b128 v[144:147], v201 offset:16384
	ds_read_b128 v[152:155], v201 offset:18432
	ds_read_b128 v[170:173], v201 offset:20480
	ds_read_b128 v[192:195], v201 offset:22528
	ds_read_b128 v[148:151], v201 offset:17408
	ds_read_b128 v[166:169], v201 offset:19456
	ds_read_b128 v[188:191], v201 offset:21504
	ds_read_b128 v[202:205], v201 offset:23552
	global_load_lds_dwordx4 v[236:237], off
	v_lshl_add_u64 v[238:239], s[52:53], 0, v[158:159]
	s_mov_b32 m0, s57
	s_nop 0
	global_load_lds_dwordx4 v[238:239], off
	s_barrier
	s_waitcnt lgkmcnt(7)
	v_mfma_f32_16x16x32_bf16 v[60:63], v[128:131], v[144:147], v[60:63]
	v_mfma_f32_16x16x32_bf16 v[52:55], v[136:139], v[144:147], v[52:55]
	s_waitcnt lgkmcnt(6)
	v_mfma_f32_16x16x32_bf16 v[44:47], v[128:131], v[152:155], v[44:47]
	v_mfma_f32_16x16x32_bf16 v[36:39], v[136:139], v[152:155], v[36:39]
	s_waitcnt lgkmcnt(5)
	v_mfma_f32_16x16x32_bf16 v[28:31], v[128:131], v[170:173], v[28:31]
	v_mfma_f32_16x16x32_bf16 v[20:23], v[136:139], v[170:173], v[20:23]
	s_waitcnt lgkmcnt(4)
	v_mfma_f32_16x16x32_bf16 v[12:15], v[128:131], v[192:195], v[12:15]
	v_mfma_f32_16x16x32_bf16 v[4:7], v[136:139], v[192:195], v[4:7]
	s_waitcnt lgkmcnt(3)
	v_mfma_f32_16x16x32_bf16 v[60:63], v[132:135], v[148:151], v[60:63]
	v_mfma_f32_16x16x32_bf16 v[52:55], v[140:143], v[148:151], v[52:55]
	s_waitcnt lgkmcnt(2)
	v_mfma_f32_16x16x32_bf16 v[44:47], v[132:135], v[166:169], v[44:47]
	v_mfma_f32_16x16x32_bf16 v[36:39], v[140:143], v[166:169], v[36:39]
	s_waitcnt lgkmcnt(1)
	v_mfma_f32_16x16x32_bf16 v[28:31], v[132:135], v[188:191], v[28:31]
	v_mfma_f32_16x16x32_bf16 v[20:23], v[140:143], v[188:191], v[20:23]
	s_waitcnt lgkmcnt(0)
	v_mfma_f32_16x16x32_bf16 v[12:15], v[132:135], v[202:205], v[12:15]
	v_mfma_f32_16x16x32_bf16 v[4:7], v[140:143], v[202:205], v[4:7]
	s_barrier
	s_add_u32 s72, s50, 0x40000
	s_addc_u32 s73, s51, 0
	s_add_i32 s28, s28, s55
	s_mov_b32 m0, s28
	s_nop 0
	global_load_lds_dwordx4 v176, s[72:73]
	s_add_i32 m0, s28, 0x2000
	s_nop 0
	global_load_lds_dwordx4 v160, s[72:73]
	s_waitcnt vmcnt(6)
	s_barrier
	v_mfma_f32_16x16x32_bf16 v[56:59], v[206:209], v[144:147], v[56:59]
	v_mfma_f32_16x16x32_bf16 v[48:51], v[214:217], v[144:147], v[48:51]
	v_mfma_f32_16x16x32_bf16 v[40:43], v[206:209], v[152:155], v[40:43]
	v_mfma_f32_16x16x32_bf16 v[32:35], v[214:217], v[152:155], v[32:35]
	v_mfma_f32_16x16x32_bf16 v[24:27], v[206:209], v[170:173], v[24:27]
	v_mfma_f32_16x16x32_bf16 v[16:19], v[214:217], v[170:173], v[16:19]
	v_mfma_f32_16x16x32_bf16 v[8:11], v[206:209], v[192:195], v[8:11]
	v_mfma_f32_16x16x32_bf16 v[0:3], v[214:217], v[192:195], v[0:3]
	v_mfma_f32_16x16x32_bf16 v[56:59], v[210:213], v[148:151], v[56:59]
	v_mfma_f32_16x16x32_bf16 v[48:51], v[232:235], v[148:151], v[48:51]
	v_mfma_f32_16x16x32_bf16 v[40:43], v[210:213], v[166:169], v[40:43]
	v_mfma_f32_16x16x32_bf16 v[32:35], v[232:235], v[166:169], v[32:35]
	v_mfma_f32_16x16x32_bf16 v[24:27], v[210:213], v[188:191], v[24:27]
	v_mfma_f32_16x16x32_bf16 v[16:19], v[232:235], v[188:191], v[16:19]
	v_mfma_f32_16x16x32_bf16 v[8:11], v[210:213], v[202:205], v[8:11]
	v_mfma_f32_16x16x32_bf16 v[0:3], v[232:235], v[202:205], v[0:3]
	s_add_i32 s28, 0, 0x18000
	v_add_u32_e32 v140, s28, v200
	s_barrier
	ds_read_b128 v[128:131], v140
	ds_read_b128 v[132:135], v140 offset:1024
	ds_read_b128 v[136:139], v140 offset:2048
	ds_read_b128 v[140:143], v140 offset:3072
	s_add_u32 s52, s52, 0x40000
	s_addc_u32 s53, s53, 0
	s_mov_b32 m0, s58
	ds_read_b128 v[144:147], v201 offset:32768
	ds_read_b128 v[152:155], v201 offset:34816
	ds_read_b128 v[170:173], v201 offset:36864
	ds_read_b128 v[192:195], v201 offset:38912
	ds_read_b128 v[148:151], v201 offset:33792
	ds_read_b128 v[166:169], v201 offset:35840
	ds_read_b128 v[188:191], v201 offset:37888
	ds_read_b128 v[202:205], v201 offset:39936
	global_load_lds_dwordx4 v156, s[52:53]
	s_mov_b32 m0, s59
	s_nop 0
	global_load_lds_dwordx4 v158, s[52:53]
	s_waitcnt lgkmcnt(8)
	s_barrier
	s_waitcnt lgkmcnt(7)
	v_mfma_f32_16x16x32_bf16 v[124:127], v[128:131], v[144:147], v[124:127]
	v_mfma_f32_16x16x32_bf16 v[116:119], v[136:139], v[144:147], v[116:119]
	s_waitcnt lgkmcnt(6)
	v_mfma_f32_16x16x32_bf16 v[108:111], v[128:131], v[152:155], v[108:111]
	v_mfma_f32_16x16x32_bf16 v[100:103], v[136:139], v[152:155], v[100:103]
	s_waitcnt lgkmcnt(5)
	v_mfma_f32_16x16x32_bf16 v[92:95], v[128:131], v[170:173], v[92:95]
	v_mfma_f32_16x16x32_bf16 v[84:87], v[136:139], v[170:173], v[84:87]
	s_waitcnt lgkmcnt(4)
	v_mfma_f32_16x16x32_bf16 v[76:79], v[128:131], v[192:195], v[76:79]
	v_mfma_f32_16x16x32_bf16 v[68:71], v[136:139], v[192:195], v[68:71]
	s_waitcnt lgkmcnt(3)
	v_mfma_f32_16x16x32_bf16 v[124:127], v[132:135], v[148:151], v[124:127]
	v_mfma_f32_16x16x32_bf16 v[116:119], v[140:143], v[148:151], v[116:119]
	s_waitcnt lgkmcnt(2)
	v_mfma_f32_16x16x32_bf16 v[108:111], v[132:135], v[166:169], v[108:111]
	v_mfma_f32_16x16x32_bf16 v[100:103], v[140:143], v[166:169], v[100:103]
	s_waitcnt lgkmcnt(1)
	v_mfma_f32_16x16x32_bf16 v[92:95], v[132:135], v[188:191], v[92:95]
	v_mfma_f32_16x16x32_bf16 v[84:87], v[140:143], v[188:191], v[84:87]
	s_waitcnt lgkmcnt(0)
	v_mfma_f32_16x16x32_bf16 v[76:79], v[132:135], v[202:205], v[76:79]
	v_mfma_f32_16x16x32_bf16 v[68:71], v[140:143], v[202:205], v[68:71]
	s_barrier
	s_add_i32 s29, 0, 0x1c000
	s_add_i32 s28, s28, s55
	v_add_u32_e32 v232, s29, v200
	v_lshl_add_u64 v[174:175], v[174:175], 0, s[40:41]
	s_mov_b32 m0, s28
	ds_read_b128 v[206:209], v232
	ds_read_b128 v[210:213], v232 offset:1024
	ds_read_b128 v[214:217], v232 offset:2048
	ds_read_b128 v[232:235], v232 offset:3072
	global_load_lds_dwordx4 v[174:175], off
	v_lshl_add_u64 v[174:175], v[196:197], 0, s[40:41]
	s_add_i32 m0, s28, 0x2000
	s_nop 0
	global_load_lds_dwordx4 v[174:175], off
	s_barrier
	s_waitcnt lgkmcnt(3)
	v_mfma_f32_16x16x32_bf16 v[120:123], v[206:209], v[144:147], v[120:123]
	s_waitcnt lgkmcnt(1)
	v_mfma_f32_16x16x32_bf16 v[112:115], v[214:217], v[144:147], v[112:115]
	v_mfma_f32_16x16x32_bf16 v[104:107], v[206:209], v[152:155], v[104:107]
	v_mfma_f32_16x16x32_bf16 v[96:99], v[214:217], v[152:155], v[96:99]
	v_mfma_f32_16x16x32_bf16 v[88:91], v[206:209], v[170:173], v[88:91]
	v_mfma_f32_16x16x32_bf16 v[80:83], v[214:217], v[170:173], v[80:83]
	v_mfma_f32_16x16x32_bf16 v[72:75], v[206:209], v[192:195], v[72:75]
	v_mfma_f32_16x16x32_bf16 v[64:67], v[214:217], v[192:195], v[64:67]
	v_mfma_f32_16x16x32_bf16 v[120:123], v[210:213], v[148:151], v[120:123]
	s_waitcnt lgkmcnt(0)
	v_mfma_f32_16x16x32_bf16 v[112:115], v[232:235], v[148:151], v[112:115]
	v_mfma_f32_16x16x32_bf16 v[104:107], v[210:213], v[166:169], v[104:107]
	v_mfma_f32_16x16x32_bf16 v[96:99], v[232:235], v[166:169], v[96:99]
	v_mfma_f32_16x16x32_bf16 v[88:91], v[210:213], v[188:191], v[88:91]
	v_mfma_f32_16x16x32_bf16 v[80:83], v[232:235], v[188:191], v[80:83]
	v_mfma_f32_16x16x32_bf16 v[72:75], v[210:213], v[202:205], v[72:75]
	v_mfma_f32_16x16x32_bf16 v[64:67], v[232:235], v[202:205], v[64:67]
	s_mov_b32 m0, s62
	v_lshl_add_u64 v[174:175], v[236:237], 0, s[40:41]
	s_barrier
	ds_read_b128 v[144:147], v201 offset:49152
	ds_read_b128 v[152:155], v201 offset:51200
	ds_read_b128 v[170:173], v201 offset:53248
	ds_read_b128 v[192:195], v201 offset:55296
	ds_read_b128 v[148:151], v201 offset:50176
	ds_read_b128 v[166:169], v201 offset:52224
	ds_read_b128 v[188:191], v201 offset:54272
	ds_read_b128 v[202:205], v201 offset:56320
	global_load_lds_dwordx4 v[174:175], off
	v_lshl_add_u64 v[174:175], v[238:239], 0, s[40:41]
	s_mov_b32 m0, s63
	s_nop 0
	global_load_lds_dwordx4 v[174:175], off
	s_barrier
	s_waitcnt lgkmcnt(7)
	v_mfma_f32_16x16x32_bf16 v[60:63], v[128:131], v[144:147], v[60:63]
	v_mfma_f32_16x16x32_bf16 v[52:55], v[136:139], v[144:147], v[52:55]
	s_waitcnt lgkmcnt(6)
	v_mfma_f32_16x16x32_bf16 v[44:47], v[128:131], v[152:155], v[44:47]
	v_mfma_f32_16x16x32_bf16 v[36:39], v[136:139], v[152:155], v[36:39]
	s_waitcnt lgkmcnt(5)
	v_mfma_f32_16x16x32_bf16 v[28:31], v[128:131], v[170:173], v[28:31]
	v_mfma_f32_16x16x32_bf16 v[20:23], v[136:139], v[170:173], v[20:23]
	s_waitcnt lgkmcnt(4)
	v_mfma_f32_16x16x32_bf16 v[12:15], v[128:131], v[192:195], v[12:15]
	v_mfma_f32_16x16x32_bf16 v[4:7], v[136:139], v[192:195], v[4:7]
	s_waitcnt lgkmcnt(3)
	v_mfma_f32_16x16x32_bf16 v[60:63], v[132:135], v[148:151], v[60:63]
	v_mfma_f32_16x16x32_bf16 v[52:55], v[140:143], v[148:151], v[52:55]
	s_waitcnt lgkmcnt(2)
	v_mfma_f32_16x16x32_bf16 v[44:47], v[132:135], v[166:169], v[44:47]
	v_mfma_f32_16x16x32_bf16 v[36:39], v[140:143], v[166:169], v[36:39]
	s_waitcnt lgkmcnt(1)
	v_mfma_f32_16x16x32_bf16 v[28:31], v[132:135], v[188:191], v[28:31]
	v_mfma_f32_16x16x32_bf16 v[20:23], v[140:143], v[188:191], v[20:23]
	s_waitcnt lgkmcnt(0)
	v_mfma_f32_16x16x32_bf16 v[12:15], v[132:135], v[202:205], v[12:15]
	v_mfma_f32_16x16x32_bf16 v[4:7], v[140:143], v[202:205], v[4:7]
	s_barrier
	s_add_u32 s50, s50, 0x40080
	s_addc_u32 s51, s51, 0
	s_add_i32 s28, s29, s55
	s_mov_b32 m0, s28
	s_nop 0
	global_load_lds_dwordx4 v176, s[50:51]
	s_add_i32 m0, s28, 0x2000
	s_nop 0
	global_load_lds_dwordx4 v160, s[50:51]
	s_waitcnt vmcnt(6)
	s_barrier
	v_mfma_f32_16x16x32_bf16 v[56:59], v[206:209], v[144:147], v[56:59]
	v_mfma_f32_16x16x32_bf16 v[48:51], v[214:217], v[144:147], v[48:51]
	v_mfma_f32_16x16x32_bf16 v[40:43], v[206:209], v[152:155], v[40:43]
	v_mfma_f32_16x16x32_bf16 v[32:35], v[214:217], v[152:155], v[32:35]
	v_mfma_f32_16x16x32_bf16 v[24:27], v[206:209], v[170:173], v[24:27]
	v_mfma_f32_16x16x32_bf16 v[16:19], v[214:217], v[170:173], v[16:19]
	v_mfma_f32_16x16x32_bf16 v[8:11], v[206:209], v[192:195], v[8:11]
	v_mfma_f32_16x16x32_bf16 v[0:3], v[214:217], v[192:195], v[0:3]
	v_mfma_f32_16x16x32_bf16 v[56:59], v[210:213], v[148:151], v[56:59]
	v_mfma_f32_16x16x32_bf16 v[48:51], v[232:235], v[148:151], v[48:51]
	v_mfma_f32_16x16x32_bf16 v[40:43], v[210:213], v[166:169], v[40:43]
	v_mfma_f32_16x16x32_bf16 v[32:35], v[232:235], v[166:169], v[32:35]
	v_mfma_f32_16x16x32_bf16 v[24:27], v[210:213], v[188:191], v[24:27]
	v_mfma_f32_16x16x32_bf16 v[16:19], v[232:235], v[188:191], v[16:19]
	v_mfma_f32_16x16x32_bf16 v[8:11], v[210:213], v[202:205], v[8:11]
	v_mfma_f32_16x16x32_bf16 v[0:3], v[232:235], v[202:205], v[0:3]
	s_add_i32 s70, s70, 2
	s_add_u32 s6, s6, 0x100
	s_addc_u32 s7, s7, 0
	s_add_u32 s68, s68, 0x100
	s_addc_u32 s69, s69, 0
	s_cmp_lt_u32 s70, 14
	s_barrier
	s_cbranch_scc1 .LBB0_1436
	v_mov_b32_e32 v134, v199
	v_mov_b32_e32 v128, v198
	s_lshl_b32 s4, s4, 8
	s_add_i32 s4, s4, s60
	v_add_u32_e32 v192, s4, v128
	v_lshlrev_b32_e32 v128, 2, v134
	v_ashrrev_i32_e32 v129, 31, v128
	v_ashrrev_i32_e32 v193, 31, v192
	v_add_u32_e32 v190, 16, v192
	v_lshl_add_u64 v[132:133], v[128:129], 2, s[8:9]
	v_lshlrev_b64 v[128:129], 6, v[192:193]
	v_ashrrev_i32_e32 v191, 31, v190
	v_add_u32_e32 v188, 32, v192
	v_lshl_add_u64 v[128:129], v[132:133], 0, v[128:129]
	v_lshlrev_b64 v[130:131], 6, v[190:191]
	v_ashrrev_i32_e32 v189, 31, v188
	v_lshl_add_u64 v[130:131], v[132:133], 0, v[130:131]
	global_load_dwordx4 v[202:205], v[128:129], off
	global_load_dwordx4 v[144:147], v[130:131], off
	v_lshlrev_b64 v[128:129], 6, v[188:189]
	v_add_u32_e32 v174, 48, v192
	v_lshl_add_u64 v[128:129], v[132:133], 0, v[128:129]
	v_ashrrev_i32_e32 v175, 31, v174
	global_load_dwordx4 v[148:151], v[128:129], off
	v_lshlrev_b64 v[128:129], 6, v[174:175]
	v_lshl_add_u64 v[128:129], v[132:133], 0, v[128:129]
	global_load_dwordx4 v[152:155], v[128:129], off
	v_add_u32_e32 v172, 0x80, v192
	v_ashrrev_i32_e32 v173, 31, v172
	v_lshlrev_b64 v[128:129], 6, v[172:173]
	v_lshl_add_u64 v[128:129], v[132:133], 0, v[128:129]
	global_load_dwordx4 v[140:143], v[128:129], off
	v_add_u32_e32 v170, 0x90, v192
	v_ashrrev_i32_e32 v171, 31, v170
	v_lshlrev_b64 v[128:129], 6, v[170:171]
	v_lshl_add_u64 v[128:129], v[132:133], 0, v[128:129]
	global_load_dwordx4 v[128:131], v[128:129], off
	s_lshl_b32 s5, s5, 7
	v_add_u32_e32 v168, 0xa0, v192
	v_add_u32_e32 v166, 0xb0, v192
	s_or_b32 s5, s5, s61
	v_ashrrev_i32_e32 v169, 31, v168
	v_ashrrev_i32_e32 v167, 31, v166
	v_lshl_add_u32 v194, v134, 3, s5
	v_lshlrev_b64 v[134:135], 6, v[168:169]
	v_lshlrev_b64 v[136:137], 6, v[166:167]
	v_lshl_add_u64 v[134:135], v[132:133], 0, v[134:135]
	v_lshl_add_u64 v[132:133], v[132:133], 0, v[136:137]
	global_load_dwordx4 v[136:139], v[134:135], off
	s_nop 0
	global_load_dwordx4 v[132:135], v[132:133], off
	s_mov_b32 s4, 0x358637bd
	v_mov_b64_e32 v[196:197], s[4:5]
	v_ashrrev_i32_e32 v195, 31, v194
	s_mov_b64 s[50:51], s[20:21]
	s_waitcnt vmcnt(0)
	v_mov_b32_e32 v206, v203
	v_mov_b32_e32 v207, v204
	v_mov_b32_e32 v203, v205
	v_mov_b32_e32 v204, v145
	v_mov_b32_e32 v205, v146
	v_mov_b32_e32 v145, v147
	v_pk_add_f32 v[202:203], v[206:207], v[202:203]
	v_mov_b32_e32 v146, v149
	v_mov_b32_e32 v147, v150
	v_mov_b32_e32 v149, v151
	v_mov_b32_e32 v150, v153
	v_mov_b32_e32 v151, v154
	v_mov_b32_e32 v153, v155
	v_pk_add_f32 v[144:145], v[204:205], v[144:145]
	v_mov_b32_e32 v155, v202
	v_pk_add_f32 v[146:147], v[146:147], v[148:149]
	v_pk_add_f32 v[148:149], v[150:151], v[152:153]
	v_mov_b32_e32 v154, v144
	v_mov_b32_e32 v202, v145
	v_mov_b32_e32 v144, v148
	v_mov_b32_e32 v145, v146
	v_mov_b32_e32 v146, v149
	v_pk_add_f32 v[148:149], v[154:155], v[202:203]
	v_pk_add_f32 v[144:145], v[144:145], v[146:147]
	ds_bpermute_b32 v147, v219, v149
	ds_bpermute_b32 v146, v219, v148
	ds_bpermute_b32 v151, v219, v145
	ds_bpermute_b32 v150, v219, v144
	v_mov_b32_e32 v152, v141
	v_mov_b32_e32 v153, v142
	v_mov_b32_e32 v141, v143
	s_waitcnt lgkmcnt(0)
	v_pk_add_f32 v[142:143], v[148:149], v[146:147]
	ds_bpermute_b32 v147, v218, v143
	ds_bpermute_b32 v146, v218, v142
	v_pk_add_f32 v[144:145], v[144:145], v[150:151]
	ds_bpermute_b32 v149, v218, v145
	ds_bpermute_b32 v148, v218, v144
	v_mov_b32_e32 v150, v129
	s_waitcnt lgkmcnt(2)
	v_pk_add_f32 v[142:143], v[142:143], v[146:147]
	v_mov_b32_e32 v151, v130
	v_pk_fma_f32 v[142:143], v[142:143], s[30:31], v[196:197] op_sel_hi:[1,0,0]
	s_waitcnt lgkmcnt(0)
	v_pk_add_f32 v[144:145], v[144:145], v[148:149]
	v_mul_f32_e32 v129, 0x4b800000, v143
	v_cmp_gt_f32_e32 vcc, s86, v143
	v_pk_fma_f32 v[146:147], v[144:145], s[30:31], v[196:197] op_sel_hi:[1,0,0]
	v_mul_f32_e32 v130, 0x4b800000, v142
	v_cndmask_b32_e32 v129, v143, v129, vcc
	v_rsq_f32_e32 v129, v129
	v_cmp_gt_f32_e64 s[4:5], s86, v142
	v_mul_f32_e32 v144, 0x4b800000, v147
	v_cmp_gt_f32_e64 s[6:7], s86, v147
	v_cndmask_b32_e64 v130, v142, v130, s[4:5]
	v_rsq_f32_e32 v142, v130
	v_cndmask_b32_e64 v130, v147, v144, s[6:7]
	v_rsq_f32_e32 v143, v130
	v_mul_f32_e32 v130, 0x45800000, v129
	v_cndmask_b32_e32 v144, v129, v130, vcc
	v_mov_b32_e32 v129, v131
	v_pk_add_f32 v[140:141], v[152:153], v[140:141]
	v_pk_add_f32 v[128:129], v[150:151], v[128:129]
	v_mov_b32_e32 v131, v140
	v_mov_b32_e32 v130, v128
	v_mov_b32_e32 v140, v129
	v_pk_add_f32 v[128:129], v[130:131], v[140:141]
	ds_bpermute_b32 v131, v219, v129
	ds_bpermute_b32 v130, v219, v128
	v_mul_f32_e32 v145, 0x45800000, v142
	v_cndmask_b32_e64 v142, v142, v145, s[4:5]
	v_mul_f32_e32 v140, 0x4b800000, v146
	v_cmp_gt_f32_e32 vcc, s86, v146
	s_waitcnt lgkmcnt(0)
	v_pk_add_f32 v[128:129], v[128:129], v[130:131]
	ds_bpermute_b32 v131, v218, v129
	ds_bpermute_b32 v130, v218, v128
	v_cndmask_b32_e32 v140, v146, v140, vcc
	v_rsq_f32_e32 v141, v140
	v_mul_f32_e32 v140, 0x45800000, v143
	v_cndmask_b32_e64 v140, v143, v140, s[6:7]
	s_waitcnt lgkmcnt(0)
	v_pk_add_f32 v[128:129], v[128:129], v[130:131]
	v_mov_b32_e32 v131, v138
	v_pk_fma_f32 v[128:129], v[128:129], s[30:31], v[196:197] op_sel_hi:[1,0,0]
	v_mul_f32_e32 v143, 0x45800000, v141
	v_mul_f32_e32 v130, 0x4b800000, v129
	v_cmp_gt_f32_e64 s[4:5], s86, v129
	v_cmp_gt_f32_e64 s[6:7], s86, v128
	v_pk_mul_f32 v[110:111], v[110:111], v[142:143] op_sel_hi:[1,0]
	v_cndmask_b32_e64 v129, v129, v130, s[4:5]
	v_mov_b32_e32 v130, v137
	v_mov_b32_e32 v137, v139
	v_pk_add_f32 v[130:131], v[130:131], v[136:137]
	v_mov_b32_e32 v136, v133
	v_mov_b32_e32 v137, v134
	v_mov_b32_e32 v133, v135
	v_pk_add_f32 v[132:133], v[136:137], v[132:133]
	v_mov_b32_e32 v135, v130
	v_mov_b32_e32 v134, v132
	v_mov_b32_e32 v130, v133
	v_pk_add_f32 v[130:131], v[134:135], v[130:131]
	ds_bpermute_b32 v133, v219, v131
	ds_bpermute_b32 v132, v219, v130
	v_rsq_f32_e32 v145, v129
	v_mul_f32_e32 v129, 0x4b800000, v128
	v_cndmask_b32_e64 v128, v128, v129, s[6:7]
	v_rsq_f32_e32 v135, v128
	s_waitcnt lgkmcnt(0)
	v_pk_add_f32 v[128:129], v[130:131], v[132:133]
	ds_bpermute_b32 v131, v218, v129
	ds_bpermute_b32 v130, v218, v128
	v_pk_mul_f32 v[126:127], v[126:127], v[144:145] op_sel_hi:[1,0]
	v_pk_mul_f32 v[122:123], v[122:123], v[144:145] op_sel_hi:[1,0]
	v_pk_mul_f32 v[116:117], v[116:117], v[144:145] op_sel_hi:[1,0]
	v_pk_mul_f32 v[124:125], v[124:125], v[144:145] op_sel_hi:[1,0]
	v_pk_mul_f32 v[138:139], v[126:127], s[44:45] op_sel_hi:[1,0]
	v_pk_mul_f32 v[120:121], v[120:121], v[144:145] op_sel_hi:[1,0]
	v_pk_mul_f32 v[122:123], v[126:127], v[122:123]
	v_pk_mul_f32 v[118:119], v[118:119], v[144:145] op_sel_hi:[1,0]
	v_pk_mul_f32 v[126:127], v[116:117], s[44:45] op_sel_hi:[1,0]
	v_pk_mul_f32 v[146:147], v[124:125], s[44:45] op_sel_hi:[1,0]
	v_pk_mul_f32 v[120:121], v[124:125], v[120:121]
	v_pk_mul_f32 v[124:125], v[118:119], s[44:45] op_sel_hi:[1,0]
	v_exp_f32_e32 v126, v126
	v_exp_f32_e32 v127, v127
	s_waitcnt lgkmcnt(0)
	v_pk_add_f32 v[128:129], v[128:129], v[130:131]
	v_exp_f32_e32 v146, v146
	v_exp_f32_e32 v138, v138
	v_exp_f32_e32 v139, v139
	v_exp_f32_e32 v147, v147
	v_exp_f32_e32 v124, v124
	v_exp_f32_e32 v125, v125
	v_pk_fma_f32 v[128:129], v[128:129], s[30:31], v[196:197] op_sel_hi:[1,0,0]
	v_cndmask_b32_e32 v136, v141, v143, vcc
	v_mul_f32_e32 v132, 0x45800000, v145
	v_mul_f32_e32 v130, 0x4b800000, v129
	v_cmp_gt_f32_e32 vcc, s86, v129
	v_cndmask_b32_e64 v134, v145, v132, s[4:5]
	v_cmp_gt_f32_e64 s[4:5], s86, v128
	v_cndmask_b32_e32 v129, v129, v130, vcc
	v_mul_f32_e32 v130, 0x4b800000, v128
	v_pk_add_f32 v[126:127], v[126:127], 1.0 op_sel_hi:[1,0]
	v_rsq_f32_e32 v129, v129
	v_cndmask_b32_e64 v128, v128, v130, s[4:5]
	v_pk_add_f32 v[138:139], v[138:139], 1.0 op_sel_hi:[1,0]
	v_pk_add_f32 v[146:147], v[146:147], 1.0 op_sel_hi:[1,0]
	v_pk_add_f32 v[124:125], v[124:125], 1.0 op_sel_hi:[1,0]
	v_rcp_f32_e32 v126, v126
	v_rcp_f32_e32 v127, v127
	v_rsq_f32_e32 v128, v128
	v_rcp_f32_e32 v146, v146
	v_rcp_f32_e32 v138, v138
	v_rcp_f32_e32 v139, v139
	v_rcp_f32_e32 v147, v147
	v_rcp_f32_e32 v124, v124
	v_rcp_f32_e32 v125, v125
	v_pk_mul_f32 v[112:113], v[112:113], v[144:145] op_sel_hi:[1,0]
	v_pk_mul_f32 v[114:115], v[114:115], v[144:145] op_sel_hi:[1,0]
	v_pk_mul_f32 v[112:113], v[116:117], v[112:113]
	v_mul_f32_e32 v130, 0x45800000, v129
	v_pk_mul_f32 v[114:115], v[118:119], v[114:115]
	v_pk_mul_f32 v[112:113], v[112:113], v[126:127]
	v_cndmask_b32_e32 v130, v129, v130, vcc
	v_mul_f32_e32 v129, 0x45800000, v128
	v_pk_mul_f32 v[122:123], v[122:123], v[138:139]
	v_pk_mul_f32 v[120:121], v[120:121], v[146:147]
	v_pk_mul_f32 v[114:115], v[114:115], v[124:125]
	v_cvt_pk_bf16_f32 v116, v120, v121
	v_cvt_pk_bf16_f32 v117, v122, v123
	v_cvt_pk_bf16_f32 v118, v112, v113
	v_mov_b64_e32 v[112:113], s[10:11]
	v_cndmask_b32_e64 v128, v128, v129, s[4:5]
	v_cvt_pk_bf16_f32 v119, v114, v115
	v_mad_i64_i32 v[120:121], s[4:5], v192, s35, v[112:113]
	v_lshlrev_b64 v[114:115], 1, v[194:195]
	v_lshl_add_u64 v[120:121], v[120:121], 0, v[114:115]
	v_pk_mul_f32 v[108:109], v[108:109], v[142:143] op_sel_hi:[1,0]
	v_pk_mul_f32 v[106:107], v[106:107], v[142:143] op_sel_hi:[1,0]
	v_pk_mul_f32 v[104:105], v[104:105], v[142:143] op_sel_hi:[1,0]
	v_pk_mul_f32 v[102:103], v[102:103], v[142:143] op_sel_hi:[1,0]
	v_pk_mul_f32 v[100:101], v[100:101], v[142:143] op_sel_hi:[1,0]
	global_store_dwordx4 v[120:121], v[116:119], off
	v_pk_mul_f32 v[104:105], v[108:109], v[104:105]
	v_pk_mul_f32 v[106:107], v[110:111], v[106:107]
	v_pk_mul_f32 v[116:117], v[110:111], s[44:45] op_sel_hi:[1,0]
	v_pk_mul_f32 v[118:119], v[108:109], s[44:45] op_sel_hi:[1,0]
	v_pk_mul_f32 v[108:109], v[102:103], s[44:45] op_sel_hi:[1,0]
	v_pk_mul_f32 v[110:111], v[100:101], s[44:45] op_sel_hi:[1,0]
	v_exp_f32_e32 v108, v108
	v_exp_f32_e32 v110, v110
	v_exp_f32_e32 v109, v109
	v_exp_f32_e32 v111, v111
	v_exp_f32_e32 v118, v118
	v_exp_f32_e32 v116, v116
	v_exp_f32_e32 v117, v117
	v_exp_f32_e32 v119, v119
	v_pk_add_f32 v[108:109], v[108:109], 1.0 op_sel_hi:[1,0]
	v_pk_add_f32 v[110:111], v[110:111], 1.0 op_sel_hi:[1,0]
	v_pk_add_f32 v[116:117], v[116:117], 1.0 op_sel_hi:[1,0]
	v_pk_add_f32 v[118:119], v[118:119], 1.0 op_sel_hi:[1,0]
	v_rcp_f32_e32 v110, v110
	v_rcp_f32_e32 v108, v108
	v_rcp_f32_e32 v109, v109
	v_rcp_f32_e32 v111, v111
	v_rcp_f32_e32 v118, v118
	v_rcp_f32_e32 v116, v116
	v_rcp_f32_e32 v117, v117
	v_rcp_f32_e32 v119, v119
	v_pk_mul_f32 v[98:99], v[98:99], v[142:143] op_sel_hi:[1,0]
	v_pk_mul_f32 v[96:97], v[96:97], v[142:143] op_sel_hi:[1,0]
	v_pk_mul_f32 v[98:99], v[102:103], v[98:99]
	v_pk_mul_f32 v[96:97], v[100:101], v[96:97]
	v_pk_mul_f32 v[100:101], v[98:99], v[108:109]
	v_pk_mul_f32 v[98:99], v[96:97], v[110:111]
	v_pk_mul_f32 v[106:107], v[106:107], v[116:117]
	v_pk_mul_f32 v[104:105], v[104:105], v[118:119]
	v_pk_mul_f32 v[94:95], v[94:95], v[140:141] op_sel_hi:[1,0]
	v_cvt_pk_bf16_f32 v96, v104, v105
	v_cvt_pk_bf16_f32 v97, v106, v107
	v_cvt_pk_bf16_f32 v98, v98, v99
	v_cvt_pk_bf16_f32 v99, v100, v101
	v_mad_i64_i32 v[100:101], s[4:5], v190, s35, v[112:113]
	v_lshl_add_u64 v[100:101], v[100:101], 0, v[114:115]
	v_pk_mul_f32 v[92:93], v[92:93], v[140:141] op_sel_hi:[1,0]
	v_pk_mul_f32 v[90:91], v[90:91], v[140:141] op_sel_hi:[1,0]
	v_pk_mul_f32 v[88:89], v[88:89], v[140:141] op_sel_hi:[1,0]
	v_pk_mul_f32 v[86:87], v[86:87], v[140:141] op_sel_hi:[1,0]
	v_pk_mul_f32 v[84:85], v[84:85], v[140:141] op_sel_hi:[1,0]
	global_store_dwordx4 v[100:101], v[96:99], off
	v_pk_mul_f32 v[88:89], v[92:93], v[88:89]
	v_pk_mul_f32 v[90:91], v[94:95], v[90:91]
	v_pk_mul_f32 v[96:97], v[94:95], s[44:45] op_sel_hi:[1,0]
	v_pk_mul_f32 v[98:99], v[92:93], s[44:45] op_sel_hi:[1,0]
	v_pk_mul_f32 v[92:93], v[86:87], s[44:45] op_sel_hi:[1,0]
	v_pk_mul_f32 v[94:95], v[84:85], s[44:45] op_sel_hi:[1,0]
	v_exp_f32_e32 v92, v92
	v_exp_f32_e32 v94, v94
	v_exp_f32_e32 v93, v93
	v_exp_f32_e32 v95, v95
	v_exp_f32_e32 v98, v98
	v_exp_f32_e32 v96, v96
	v_exp_f32_e32 v97, v97
	v_exp_f32_e32 v99, v99
	v_pk_add_f32 v[92:93], v[92:93], 1.0 op_sel_hi:[1,0]
	v_pk_add_f32 v[94:95], v[94:95], 1.0 op_sel_hi:[1,0]
	v_pk_add_f32 v[96:97], v[96:97], 1.0 op_sel_hi:[1,0]
	v_pk_add_f32 v[98:99], v[98:99], 1.0 op_sel_hi:[1,0]
	v_rcp_f32_e32 v94, v94
	v_rcp_f32_e32 v92, v92
	v_rcp_f32_e32 v93, v93
	v_rcp_f32_e32 v95, v95
	v_rcp_f32_e32 v98, v98
	v_rcp_f32_e32 v96, v96
	v_rcp_f32_e32 v97, v97
	v_rcp_f32_e32 v99, v99
	v_pk_mul_f32 v[82:83], v[82:83], v[140:141] op_sel_hi:[1,0]
	v_pk_mul_f32 v[80:81], v[80:81], v[140:141] op_sel_hi:[1,0]
	v_pk_mul_f32 v[82:83], v[86:87], v[82:83]
	v_pk_mul_f32 v[80:81], v[84:85], v[80:81]
	v_pk_mul_f32 v[84:85], v[82:83], v[92:93]
	v_pk_mul_f32 v[82:83], v[80:81], v[94:95]
	v_pk_mul_f32 v[90:91], v[90:91], v[96:97]
	v_pk_mul_f32 v[88:89], v[88:89], v[98:99]
	v_pk_mul_f32 v[78:79], v[78:79], v[136:137] op_sel_hi:[1,0]
	v_cvt_pk_bf16_f32 v80, v88, v89
	v_cvt_pk_bf16_f32 v81, v90, v91
	v_cvt_pk_bf16_f32 v82, v82, v83
	v_cvt_pk_bf16_f32 v83, v84, v85
	v_mad_i64_i32 v[84:85], s[4:5], v188, s35, v[112:113]
	v_lshl_add_u64 v[84:85], v[84:85], 0, v[114:115]
	v_pk_mul_f32 v[76:77], v[76:77], v[136:137] op_sel_hi:[1,0]
	v_pk_mul_f32 v[74:75], v[74:75], v[136:137] op_sel_hi:[1,0]
	v_pk_mul_f32 v[72:73], v[72:73], v[136:137] op_sel_hi:[1,0]
	v_pk_mul_f32 v[70:71], v[70:71], v[136:137] op_sel_hi:[1,0]
	v_pk_mul_f32 v[68:69], v[68:69], v[136:137] op_sel_hi:[1,0]
	global_store_dwordx4 v[84:85], v[80:83], off
	v_pk_mul_f32 v[72:73], v[76:77], v[72:73]
	v_pk_mul_f32 v[74:75], v[78:79], v[74:75]
	v_pk_mul_f32 v[80:81], v[78:79], s[44:45] op_sel_hi:[1,0]
	v_pk_mul_f32 v[82:83], v[76:77], s[44:45] op_sel_hi:[1,0]
	v_pk_mul_f32 v[76:77], v[70:71], s[44:45] op_sel_hi:[1,0]
	v_pk_mul_f32 v[78:79], v[68:69], s[44:45] op_sel_hi:[1,0]
	v_exp_f32_e32 v76, v76
	v_exp_f32_e32 v78, v78
	v_exp_f32_e32 v77, v77
	v_exp_f32_e32 v79, v79
	v_exp_f32_e32 v82, v82
	v_exp_f32_e32 v80, v80
	v_exp_f32_e32 v81, v81
	v_exp_f32_e32 v83, v83
	v_pk_add_f32 v[76:77], v[76:77], 1.0 op_sel_hi:[1,0]
	v_pk_add_f32 v[78:79], v[78:79], 1.0 op_sel_hi:[1,0]
	v_pk_add_f32 v[80:81], v[80:81], 1.0 op_sel_hi:[1,0]
	v_pk_add_f32 v[82:83], v[82:83], 1.0 op_sel_hi:[1,0]
	v_rcp_f32_e32 v78, v78
	v_rcp_f32_e32 v76, v76
	v_rcp_f32_e32 v77, v77
	v_rcp_f32_e32 v79, v79
	v_rcp_f32_e32 v82, v82
	v_rcp_f32_e32 v80, v80
	v_rcp_f32_e32 v81, v81
	v_rcp_f32_e32 v83, v83
	v_pk_mul_f32 v[66:67], v[66:67], v[136:137] op_sel_hi:[1,0]
	v_pk_mul_f32 v[64:65], v[64:65], v[136:137] op_sel_hi:[1,0]
	v_pk_mul_f32 v[66:67], v[70:71], v[66:67]
	v_pk_mul_f32 v[64:65], v[68:69], v[64:65]
	v_pk_mul_f32 v[68:69], v[66:67], v[76:77]
	v_pk_mul_f32 v[66:67], v[64:65], v[78:79]
	v_pk_mul_f32 v[74:75], v[74:75], v[80:81]
	v_pk_mul_f32 v[72:73], v[72:73], v[82:83]
	v_pk_mul_f32 v[62:63], v[62:63], v[134:135] op_sel_hi:[1,0]
	v_cvt_pk_bf16_f32 v64, v72, v73
	v_cvt_pk_bf16_f32 v65, v74, v75
	v_cvt_pk_bf16_f32 v66, v66, v67
	v_cvt_pk_bf16_f32 v67, v68, v69
	v_mad_i64_i32 v[68:69], s[4:5], v174, s35, v[112:113]
	v_lshl_add_u64 v[68:69], v[68:69], 0, v[114:115]
	v_pk_mul_f32 v[60:61], v[60:61], v[134:135] op_sel_hi:[1,0]
	v_pk_mul_f32 v[58:59], v[58:59], v[134:135] op_sel_hi:[1,0]
	v_pk_mul_f32 v[56:57], v[56:57], v[134:135] op_sel_hi:[1,0]
	v_pk_mul_f32 v[54:55], v[54:55], v[134:135] op_sel_hi:[1,0]
	v_pk_mul_f32 v[52:53], v[52:53], v[134:135] op_sel_hi:[1,0]
	global_store_dwordx4 v[68:69], v[64:67], off
	v_pk_mul_f32 v[56:57], v[60:61], v[56:57]
	v_pk_mul_f32 v[58:59], v[62:63], v[58:59]
	v_pk_mul_f32 v[64:65], v[62:63], s[44:45] op_sel_hi:[1,0]
	v_pk_mul_f32 v[66:67], v[60:61], s[44:45] op_sel_hi:[1,0]
	v_pk_mul_f32 v[60:61], v[54:55], s[44:45] op_sel_hi:[1,0]
	v_pk_mul_f32 v[62:63], v[52:53], s[44:45] op_sel_hi:[1,0]
	v_exp_f32_e32 v60, v60
	v_exp_f32_e32 v62, v62
	v_exp_f32_e32 v61, v61
	v_exp_f32_e32 v63, v63
	v_exp_f32_e32 v66, v66
	v_exp_f32_e32 v64, v64
	v_exp_f32_e32 v65, v65
	v_exp_f32_e32 v67, v67
	v_pk_add_f32 v[60:61], v[60:61], 1.0 op_sel_hi:[1,0]
	v_pk_add_f32 v[62:63], v[62:63], 1.0 op_sel_hi:[1,0]
	v_pk_add_f32 v[64:65], v[64:65], 1.0 op_sel_hi:[1,0]
	v_pk_add_f32 v[66:67], v[66:67], 1.0 op_sel_hi:[1,0]
	v_rcp_f32_e32 v62, v62
	v_rcp_f32_e32 v60, v60
	v_rcp_f32_e32 v61, v61
	v_rcp_f32_e32 v63, v63
	v_rcp_f32_e32 v66, v66
	v_rcp_f32_e32 v64, v64
	v_rcp_f32_e32 v65, v65
	v_rcp_f32_e32 v67, v67
	v_pk_mul_f32 v[50:51], v[50:51], v[134:135] op_sel_hi:[1,0]
	v_pk_mul_f32 v[48:49], v[48:49], v[134:135] op_sel_hi:[1,0]
	v_pk_mul_f32 v[50:51], v[54:55], v[50:51]
	v_pk_mul_f32 v[48:49], v[52:53], v[48:49]
	v_mul_f32_e32 v132, 0x45800000, v135
	v_pk_mul_f32 v[52:53], v[50:51], v[60:61]
	v_pk_mul_f32 v[50:51], v[48:49], v[62:63]
	v_cndmask_b32_e64 v132, v135, v132, s[6:7]
	v_pk_mul_f32 v[58:59], v[58:59], v[64:65]
	v_pk_mul_f32 v[56:57], v[56:57], v[66:67]
	v_pk_mul_f32 v[46:47], v[46:47], v[132:133] op_sel_hi:[1,0]
	v_cvt_pk_bf16_f32 v48, v56, v57
	v_cvt_pk_bf16_f32 v49, v58, v59
	v_cvt_pk_bf16_f32 v50, v50, v51
	v_cvt_pk_bf16_f32 v51, v52, v53
	v_mad_i64_i32 v[52:53], s[4:5], v172, s35, v[112:113]
	v_lshl_add_u64 v[52:53], v[52:53], 0, v[114:115]
	v_pk_mul_f32 v[44:45], v[44:45], v[132:133] op_sel_hi:[1,0]
	v_pk_mul_f32 v[42:43], v[42:43], v[132:133] op_sel_hi:[1,0]
	v_pk_mul_f32 v[40:41], v[40:41], v[132:133] op_sel_hi:[1,0]
	v_pk_mul_f32 v[38:39], v[38:39], v[132:133] op_sel_hi:[1,0]
	v_pk_mul_f32 v[36:37], v[36:37], v[132:133] op_sel_hi:[1,0]
	global_store_dwordx4 v[52:53], v[48:51], off
	v_pk_mul_f32 v[40:41], v[44:45], v[40:41]
	v_pk_mul_f32 v[42:43], v[46:47], v[42:43]
	v_pk_mul_f32 v[48:49], v[46:47], s[44:45] op_sel_hi:[1,0]
	v_pk_mul_f32 v[50:51], v[44:45], s[44:45] op_sel_hi:[1,0]
	v_pk_mul_f32 v[44:45], v[38:39], s[44:45] op_sel_hi:[1,0]
	v_pk_mul_f32 v[46:47], v[36:37], s[44:45] op_sel_hi:[1,0]
	v_exp_f32_e32 v44, v44
	v_exp_f32_e32 v46, v46
	v_exp_f32_e32 v45, v45
	v_exp_f32_e32 v47, v47
	v_exp_f32_e32 v50, v50
	v_exp_f32_e32 v48, v48
	v_exp_f32_e32 v49, v49
	v_exp_f32_e32 v51, v51
	v_pk_add_f32 v[44:45], v[44:45], 1.0 op_sel_hi:[1,0]
	v_pk_add_f32 v[46:47], v[46:47], 1.0 op_sel_hi:[1,0]
	v_pk_add_f32 v[48:49], v[48:49], 1.0 op_sel_hi:[1,0]
	v_pk_add_f32 v[50:51], v[50:51], 1.0 op_sel_hi:[1,0]
	v_rcp_f32_e32 v46, v46
	v_rcp_f32_e32 v44, v44
	v_rcp_f32_e32 v45, v45
	v_rcp_f32_e32 v47, v47
	v_rcp_f32_e32 v50, v50
	v_rcp_f32_e32 v48, v48
	v_rcp_f32_e32 v49, v49
	v_rcp_f32_e32 v51, v51
	v_pk_mul_f32 v[34:35], v[34:35], v[132:133] op_sel_hi:[1,0]
	v_pk_mul_f32 v[32:33], v[32:33], v[132:133] op_sel_hi:[1,0]
	v_pk_mul_f32 v[34:35], v[38:39], v[34:35]
	v_pk_mul_f32 v[32:33], v[36:37], v[32:33]
	v_pk_mul_f32 v[36:37], v[34:35], v[44:45]
	v_pk_mul_f32 v[34:35], v[32:33], v[46:47]
	v_pk_mul_f32 v[42:43], v[42:43], v[48:49]
	v_pk_mul_f32 v[40:41], v[40:41], v[50:51]
	v_pk_mul_f32 v[30:31], v[30:31], v[130:131] op_sel_hi:[1,0]
	v_cvt_pk_bf16_f32 v32, v40, v41
	v_cvt_pk_bf16_f32 v33, v42, v43
	v_cvt_pk_bf16_f32 v34, v34, v35
	v_cvt_pk_bf16_f32 v35, v36, v37
	v_mad_i64_i32 v[36:37], s[4:5], v170, s35, v[112:113]
	v_lshl_add_u64 v[36:37], v[36:37], 0, v[114:115]
	v_pk_mul_f32 v[28:29], v[28:29], v[130:131] op_sel_hi:[1,0]
	v_pk_mul_f32 v[26:27], v[26:27], v[130:131] op_sel_hi:[1,0]
	v_pk_mul_f32 v[24:25], v[24:25], v[130:131] op_sel_hi:[1,0]
	v_pk_mul_f32 v[22:23], v[22:23], v[130:131] op_sel_hi:[1,0]
	v_pk_mul_f32 v[20:21], v[20:21], v[130:131] op_sel_hi:[1,0]
	global_store_dwordx4 v[36:37], v[32:35], off
	v_pk_mul_f32 v[24:25], v[28:29], v[24:25]
	v_pk_mul_f32 v[26:27], v[30:31], v[26:27]
	v_pk_mul_f32 v[32:33], v[30:31], s[44:45] op_sel_hi:[1,0]
	v_pk_mul_f32 v[34:35], v[28:29], s[44:45] op_sel_hi:[1,0]
	v_pk_mul_f32 v[28:29], v[22:23], s[44:45] op_sel_hi:[1,0]
	v_pk_mul_f32 v[30:31], v[20:21], s[44:45] op_sel_hi:[1,0]
	v_exp_f32_e32 v28, v28
	v_exp_f32_e32 v30, v30
	v_exp_f32_e32 v29, v29
	v_exp_f32_e32 v31, v31
	v_exp_f32_e32 v34, v34
	v_exp_f32_e32 v32, v32
	v_exp_f32_e32 v33, v33
	v_exp_f32_e32 v35, v35
	v_pk_add_f32 v[28:29], v[28:29], 1.0 op_sel_hi:[1,0]
	v_pk_add_f32 v[30:31], v[30:31], 1.0 op_sel_hi:[1,0]
	v_pk_add_f32 v[32:33], v[32:33], 1.0 op_sel_hi:[1,0]
	v_pk_add_f32 v[34:35], v[34:35], 1.0 op_sel_hi:[1,0]
	v_rcp_f32_e32 v30, v30
	v_rcp_f32_e32 v28, v28
	v_rcp_f32_e32 v29, v29
	v_rcp_f32_e32 v31, v31
	v_rcp_f32_e32 v34, v34
	v_rcp_f32_e32 v32, v32
	v_rcp_f32_e32 v33, v33
	v_rcp_f32_e32 v35, v35
	v_pk_mul_f32 v[18:19], v[18:19], v[130:131] op_sel_hi:[1,0]
	v_pk_mul_f32 v[16:17], v[16:17], v[130:131] op_sel_hi:[1,0]
	v_pk_mul_f32 v[18:19], v[22:23], v[18:19]
	v_pk_mul_f32 v[16:17], v[20:21], v[16:17]
	v_pk_mul_f32 v[20:21], v[18:19], v[28:29]
	v_pk_mul_f32 v[18:19], v[16:17], v[30:31]
	v_pk_mul_f32 v[26:27], v[26:27], v[32:33]
	v_pk_mul_f32 v[24:25], v[24:25], v[34:35]
	v_pk_mul_f32 v[14:15], v[14:15], v[128:129] op_sel_hi:[1,0]
	v_cvt_pk_bf16_f32 v16, v24, v25
	v_cvt_pk_bf16_f32 v17, v26, v27
	v_cvt_pk_bf16_f32 v18, v18, v19
	v_cvt_pk_bf16_f32 v19, v20, v21
	v_mad_i64_i32 v[20:21], s[4:5], v168, s35, v[112:113]
	v_lshl_add_u64 v[20:21], v[20:21], 0, v[114:115]
	v_pk_mul_f32 v[12:13], v[12:13], v[128:129] op_sel_hi:[1,0]
	v_pk_mul_f32 v[10:11], v[10:11], v[128:129] op_sel_hi:[1,0]
	v_pk_mul_f32 v[8:9], v[8:9], v[128:129] op_sel_hi:[1,0]
	v_pk_mul_f32 v[6:7], v[6:7], v[128:129] op_sel_hi:[1,0]
	v_pk_mul_f32 v[4:5], v[4:5], v[128:129] op_sel_hi:[1,0]
	global_store_dwordx4 v[20:21], v[16:19], off
	v_pk_mul_f32 v[8:9], v[12:13], v[8:9]
	v_pk_mul_f32 v[10:11], v[14:15], v[10:11]
	v_pk_mul_f32 v[16:17], v[14:15], s[44:45] op_sel_hi:[1,0]
	v_pk_mul_f32 v[18:19], v[12:13], s[44:45] op_sel_hi:[1,0]
	v_pk_mul_f32 v[12:13], v[6:7], s[44:45] op_sel_hi:[1,0]
	v_pk_mul_f32 v[14:15], v[4:5], s[44:45] op_sel_hi:[1,0]
	v_exp_f32_e32 v12, v12
	v_exp_f32_e32 v14, v14
	v_exp_f32_e32 v13, v13
	v_exp_f32_e32 v15, v15
	v_exp_f32_e32 v18, v18
	v_exp_f32_e32 v16, v16
	v_exp_f32_e32 v17, v17
	v_exp_f32_e32 v19, v19
	v_pk_add_f32 v[12:13], v[12:13], 1.0 op_sel_hi:[1,0]
	v_pk_add_f32 v[14:15], v[14:15], 1.0 op_sel_hi:[1,0]
	v_pk_add_f32 v[16:17], v[16:17], 1.0 op_sel_hi:[1,0]
	v_pk_add_f32 v[18:19], v[18:19], 1.0 op_sel_hi:[1,0]
	v_rcp_f32_e32 v14, v14
	v_rcp_f32_e32 v12, v12
	v_rcp_f32_e32 v13, v13
	v_rcp_f32_e32 v15, v15
	v_rcp_f32_e32 v18, v18
	v_rcp_f32_e32 v16, v16
	v_rcp_f32_e32 v17, v17
	v_rcp_f32_e32 v19, v19
	v_pk_mul_f32 v[2:3], v[2:3], v[128:129] op_sel_hi:[1,0]
	v_pk_mul_f32 v[0:1], v[0:1], v[128:129] op_sel_hi:[1,0]
	v_pk_mul_f32 v[2:3], v[6:7], v[2:3]
	v_pk_mul_f32 v[0:1], v[4:5], v[0:1]
	v_pk_mul_f32 v[4:5], v[2:3], v[12:13]
	v_pk_mul_f32 v[2:3], v[0:1], v[14:15]
	v_pk_mul_f32 v[10:11], v[10:11], v[16:17]
	v_pk_mul_f32 v[8:9], v[8:9], v[18:19]
	s_andn2_b64 vcc, exec, s[2:3]
	v_cvt_pk_bf16_f32 v0, v8, v9
	v_cvt_pk_bf16_f32 v1, v10, v11
	v_cvt_pk_bf16_f32 v2, v2, v3
	v_cvt_pk_bf16_f32 v3, v4, v5
	v_mad_i64_i32 v[4:5], s[4:5], v166, s35, v[112:113]
	v_lshl_add_u64 v[4:5], v[4:5], 0, v[114:115]
	s_mov_b32 s4, s16
	s_mov_b32 s5, s12
	s_mov_b64 s[6:7], s[18:19]
	global_store_dwordx4 v[4:5], v[0:3], off
	s_cbranch_vccnz .LBB0_1429
	s_waitcnt vmcnt(0)
	s_cmpk_gt_u32 s24, 0xff
	s_cbranch_scc1 .LBB0_1440
	s_barrier
